# compressed-branch softmax numerators: 15 LDS bias lookups in flight + sign-mask instead of 64 serialized exec-masked lookups
# speedup vs baseline: 1.0389x; 1.0053x over previous
.LBB0_48:
	v_readlane_b32 s0, v252, 57
	s_bfe_u32 s4, s0, 0x70001
	s_bfe_u32 s0, s0, 0x20001
	v_lshl_add_u32 v2, s0, 9, v172
	v_readlane_b32 s2, v252, 62
	v_ashrrev_i32_e32 v3, 31, v2
	v_readlane_b32 s3, v252, 63
	s_waitcnt vmcnt(2)
	v_and_b32_e32 v47, 0xffff0000, v103
	v_writelane_b32 v253, s0, 0
	v_lshl_add_u64 v[2:3], v[2:3], 2, s[2:3]
	global_load_dword v1, v[2:3], off
	v_readlane_b32 s0, v252, 58
	v_readlane_b32 s1, v252, 59
	v_and_b32_e32 v2, 64, v209
	s_load_dwordx2 s[0:1], s[0:1], 0xf0
	v_add_u32_e32 v195, 64, v2
	v_lshlrev_b32_e32 v46, 16, v103
	v_mul_f32_e32 v50, v47, v47
	v_pk_fma_f32 v[58:59], v[46:47], v[46:47], v[50:51] op_sel_hi:[1,1,0]
	v_and_b32_e32 v51, 0xffff0000, v102
	v_lshlrev_b32_e32 v50, 16, v102
	v_mul_f32_e32 v54, v51, v51
	v_pk_fma_f32 v[60:61], v[50:51], v[50:51], v[54:55] op_sel_hi:[1,1,0]
	v_and_b32_e32 v55, 0xffff0000, v101
	v_and_b32_e32 v57, 0xffff0000, v100
	v_lshlrev_b32_e32 v54, 16, v101
	v_lshlrev_b32_e32 v56, 16, v100
	v_mov_b32_e32 v64, v55
	v_mov_b32_e32 v65, v57
	v_mov_b32_e32 v62, v54
	v_mov_b32_e32 v63, v56
	v_pk_mul_f32 v[64:65], v[64:65], v[64:65]
	v_and_b32_e32 v77, 0xffff0000, v106
	v_pk_fma_f32 v[66:67], v[62:63], v[62:63], v[64:65]
	v_and_b32_e32 v63, 0xffff0000, v99
	v_and_b32_e32 v65, 0xffff0000, v98
	v_lshlrev_b32_e32 v62, 16, v99
	v_lshlrev_b32_e32 v64, 16, v98
	v_mov_b32_e32 v70, v65
	v_mov_b32_e32 v71, v63
	v_mov_b32_e32 v68, v64
	v_mov_b32_e32 v69, v62
	v_pk_mul_f32 v[70:71], v[70:71], v[70:71]
	v_lshlrev_b32_e32 v76, 16, v106
	v_pk_fma_f32 v[68:69], v[68:69], v[68:69], v[70:71]
	v_and_b32_e32 v71, 0xffff0000, v108
	v_pk_add_f32 v[68:69], v[68:69], v[68:69] op_sel:[0,1] op_sel_hi:[1,0]
	v_lshlrev_b32_e32 v70, 16, v108
	v_pk_add_f32 v[68:69], v[66:67], v[68:69] op_sel:[1,0] op_sel_hi:[0,1]
	v_pk_add_f32 v[66:67], v[66:67], v[68:69]
	v_and_b32_e32 v69, 0xffff0000, v109
	v_lshlrev_b32_e32 v68, 16, v109
	v_mov_b32_e32 v74, v69
	v_mov_b32_e32 v75, v71
	v_mov_b32_e32 v72, v68
	v_mov_b32_e32 v73, v70
	v_pk_mul_f32 v[74:75], v[74:75], v[74:75]
	v_mov_b32_e32 v80, v77
	v_pk_fma_f32 v[72:73], v[72:73], v[72:73], v[74:75]
	v_and_b32_e32 v75, 0xffff0000, v107
	v_lshlrev_b32_e32 v74, 16, v107
	v_mov_b32_e32 v81, v75
	v_mov_b32_e32 v78, v76
	v_mov_b32_e32 v79, v74
	v_pk_mul_f32 v[80:81], v[80:81], v[80:81]
	s_waitcnt vmcnt(2)
	v_and_b32_e32 v37, 0xffff0000, v112
	v_pk_fma_f32 v[78:79], v[78:79], v[78:79], v[80:81]
	v_and_b32_e32 v43, 0xffff0000, v105
	v_pk_add_f32 v[78:79], v[78:79], v[78:79] op_sel:[0,1] op_sel_hi:[1,0]
	v_lshlrev_b32_e32 v36, 16, v112
	v_lshlrev_b32_e32 v38, 16, v111
	v_and_b32_e32 v39, 0xffff0000, v111
	v_and_b32_e32 v41, 0xffff0000, v110
	v_lshlrev_b32_e32 v42, 16, v105
	v_and_b32_e32 v45, 0xffff0000, v104
	v_pk_add_f32 v[78:79], v[72:73], v[78:79] op_sel:[1,0] op_sel_hi:[0,1]
	v_mov_b32_e32 v80, v43
	v_mov_b32_e32 v81, v37
	v_pk_mul_f32 v[52:53], v[38:39], v[38:39]
	v_lshlrev_b32_e32 v40, 16, v110
	v_lshlrev_b32_e32 v44, 16, v104
	v_pk_add_f32 v[72:73], v[72:73], v[78:79]
	v_mov_b32_e32 v78, v42
	v_mov_b32_e32 v79, v36
	v_pk_mul_f32 v[80:81], v[80:81], v[80:81]
	v_mov_b32_e32 v82, v45
	v_mov_b32_e32 v83, v41
	v_lshlrev_b32_e32 v34, 16, v113
	v_and_b32_e32 v35, 0xffff0000, v113
	v_pk_fma_f32 v[78:79], v[78:79], v[78:79], v[80:81]
	s_waitcnt vmcnt(0)
	v_mul_f32_e32 v1, 0x3fb8aa3b, v1
	ds_write_b32 v169, v1
	v_lshrrev_b32_e32 v2, 7, v172
	v_lshlrev_b32_e32 v3, 2, v172
	v_lshl_add_u32 v3, v2, 9, v3
	v_bfe_u32 v4, v172, 6, 1
	v_readlane_b32 s100, v1, 63
	v_add_u32_e32 v5, 0x22200, v3
	ds_write_b32 v5, v1
	v_lshl_add_u32 v3, v4, 9, v3
	v_cmp_ne_u32_e32 vcc, 0, v4
	v_mov_b32_e32 v5, s100
	v_add_u32_e32 v3, 0x22100, v3
	v_cndmask_b32_e32 v5, v210, v5, vcc
	ds_write_b32 v3, v5
	v_xor_b32_e32 v1, 32, v209
	v_cmp_lt_i32_e32 vcc, v1, v195
	v_mov_b32_e32 v80, v44
	v_mov_b32_e32 v81, v40
	v_cndmask_b32_e32 v1, v209, v1, vcc
	v_lshlrev_b32_e32 v163, 2, v1
	v_lshlrev_b32_e32 v1, 2, v174
	s_waitcnt lgkmcnt(0)
	global_load_dwordx4 v[26:29], v1, s[0:1] offset:16
	global_load_dwordx4 v[30:33], v1, s[0:1]
	global_load_dwordx4 v[18:21], v1, s[0:1] offset:80
	global_load_dwordx4 v[22:25], v1, s[0:1] offset:64
	global_load_dwordx4 v[10:13], v1, s[0:1] offset:144
	global_load_dwordx4 v[14:17], v1, s[0:1] offset:128
	global_load_dwordx4 v[2:5], v1, s[0:1] offset:208
	global_load_dwordx4 v[6:9], v1, s[0:1] offset:192
	v_pk_mul_f32 v[82:83], v[82:83], v[82:83]
	v_mov_b32_e32 v61, v52
	v_mov_b32_e32 v59, v53
	v_pk_mul_f32 v[48:49], v[34:35], v[34:35]
	v_pk_fma_f32 v[80:81], v[80:81], v[80:81], v[82:83]
	v_pk_add_f32 v[52:53], v[60:61], v[58:59]
	v_mov_b32_e32 v73, v48
	v_pk_add_f32 v[52:53], v[80:81], v[52:53]
	v_mov_b32_e32 v67, v49
	v_pk_add_f32 v[52:53], v[78:79], v[52:53]
	v_pk_add_f32 v[48:49], v[72:73], v[66:67]
	s_mov_b32 s0, 0x800000
	v_pk_add_f32 v[48:49], v[48:49], v[52:53]
	s_lshl_b32 s5, s50, 6
	v_add_f32_e32 v1, v48, v49
	ds_bpermute_b32 v48, v163, v1
	v_lshlrev_b32_e32 v96, 1, v174
	v_mov_b32_e32 v187, v97
	s_waitcnt lgkmcnt(0)
	s_barrier
	v_add_f32_e32 v1, v1, v48
	v_fmamk_f32 v1, v1, 0x3c800000, v207
	v_cmp_gt_f32_e32 vcc, s0, v1
	v_mul_f32_e32 v48, 0x4b800000, v1
	s_lshl_b32 s0, s4, 14
	v_cndmask_b32_e32 v1, v1, v48, vcc
	v_rsq_f32_e32 v1, v1
	s_add_u32 s0, s2, s0
	s_addc_u32 s1, s3, 0
	v_mul_f32_e32 v48, 0x45800000, v1
	v_cndmask_b32_e32 v1, v1, v48, vcc
	v_mul_f32_e32 v48, 0x3e38aa3b, v1
	v_pk_mul_f32 v[52:53], v[48:49], v[76:77] op_sel_hi:[0,1]
	v_mul_f32_e32 v0, 0xbfb8aa3b, v164
	v_writelane_b32 v253, s4, 1
	s_waitcnt vmcnt(6)
	v_pk_mul_f32 v[30:31], v[30:31], v[52:53]
	s_nop 0
	v_cvt_pk_bf16_f32 v114, v30, v31
	v_pk_mul_f32 v[30:31], v[48:49], v[74:75] op_sel_hi:[0,1]
	v_pk_mul_f32 v[30:31], v[32:33], v[30:31]
	s_nop 0
	v_cvt_pk_bf16_f32 v115, v30, v31
	v_pk_mul_f32 v[30:31], v[48:49], v[70:71] op_sel_hi:[0,1]
	v_pk_mul_f32 v[26:27], v[26:27], v[30:31]
	s_nop 0
	v_cvt_pk_bf16_f32 v116, v26, v27
	v_pk_mul_f32 v[26:27], v[48:49], v[68:69] op_sel_hi:[0,1]
	v_pk_mul_f32 v[26:27], v[28:29], v[26:27]
	s_nop 0
	v_cvt_pk_bf16_f32 v117, v26, v27
	v_pk_mul_f32 v[26:27], v[48:49], v[64:65] op_sel_hi:[0,1]
	s_waitcnt vmcnt(4)
	v_pk_mul_f32 v[22:23], v[22:23], v[26:27]
	s_nop 0
	v_cvt_pk_bf16_f32 v118, v22, v23
	v_pk_mul_f32 v[22:23], v[48:49], v[62:63] op_sel_hi:[0,1]
	v_pk_mul_f32 v[22:23], v[24:25], v[22:23]
	s_nop 0
	v_cvt_pk_bf16_f32 v119, v22, v23
	v_pk_mul_f32 v[22:23], v[48:49], v[56:57] op_sel_hi:[0,1]
	v_pk_mul_f32 v[18:19], v[18:19], v[22:23]
	s_nop 0
	v_cvt_pk_bf16_f32 v120, v18, v19
	v_pk_mul_f32 v[18:19], v[48:49], v[54:55] op_sel_hi:[0,1]
	v_pk_mul_f32 v[18:19], v[20:21], v[18:19]
	s_nop 0
	v_cvt_pk_bf16_f32 v121, v18, v19
	v_pk_mul_f32 v[18:19], v[48:49], v[50:51] op_sel_hi:[0,1]
	s_waitcnt vmcnt(2)
	v_pk_mul_f32 v[14:15], v[14:15], v[18:19]
	s_nop 0
	v_cvt_pk_bf16_f32 v122, v14, v15
	v_pk_mul_f32 v[14:15], v[48:49], v[46:47] op_sel_hi:[0,1]
	v_pk_mul_f32 v[14:15], v[16:17], v[14:15]
	s_nop 0
	v_cvt_pk_bf16_f32 v123, v14, v15
	v_pk_mul_f32 v[14:15], v[48:49], v[44:45] op_sel_hi:[0,1]
	v_pk_mul_f32 v[10:11], v[10:11], v[14:15]
	s_nop 0
	v_cvt_pk_bf16_f32 v124, v10, v11
	v_pk_mul_f32 v[10:11], v[48:49], v[42:43] op_sel_hi:[0,1]
	v_pk_mul_f32 v[10:11], v[12:13], v[10:11]
	s_nop 0
	v_cvt_pk_bf16_f32 v125, v10, v11
	v_pk_mul_f32 v[10:11], v[48:49], v[40:41] op_sel_hi:[0,1]
	s_waitcnt vmcnt(0)
	v_pk_mul_f32 v[6:7], v[6:7], v[10:11]
	s_nop 0
	v_cvt_pk_bf16_f32 v126, v6, v7
	v_pk_mul_f32 v[6:7], v[48:49], v[38:39] op_sel_hi:[0,1]
	v_pk_mul_f32 v[6:7], v[8:9], v[6:7]
	s_nop 0
	v_cvt_pk_bf16_f32 v127, v6, v7
	v_pk_mul_f32 v[6:7], v[48:49], v[36:37] op_sel_hi:[0,1]
	v_pk_mul_f32 v[2:3], v[2:3], v[6:7]
	s_nop 0
	v_cvt_pk_bf16_f32 v128, v2, v3
	v_pk_mul_f32 v[2:3], v[48:49], v[34:35] op_sel_hi:[0,1]
	v_pk_mul_f32 v[2:3], v[4:5], v[2:3]
	s_nop 0
	v_cvt_pk_bf16_f32 v129, v2, v3
	v_lshl_add_u64 v[2:3], s[0:1], 0, v[96:97]
	v_lshl_add_u64 v[80:81], v[2:3], 0, v[186:187]
	s_mov_b64 s[0:1], 0x5000000
	v_lshl_add_u64 v[2:3], v[80:81], 0, s[0:1]
	s_mov_b32 s0, 0x5001000
	v_add_co_u32_e32 v4, vcc, s0, v80
	s_nop 1
	v_addc_co_u32_e32 v5, vcc, 0, v81, vcc
	global_load_dwordx4 v[16:19], v[4:5], off offset:-4096
	global_load_dwordx4 v[24:27], v[2:3], off offset:32
	global_load_dwordx4 v[20:23], v[2:3], off offset:64
	global_load_dwordx4 v[28:31], v[2:3], off offset:96
	global_load_dwordx4 v[64:67], v[4:5], off
	global_load_dwordx4 v[68:71], v[4:5], off offset:32
	global_load_dwordx4 v[72:75], v[4:5], off offset:64
	global_load_dwordx4 v[76:79], v[4:5], off offset:96
	v_mov_b32_e32 v1, v0
	v_mov_b32_e32 v2, v0
	v_mov_b32_e32 v3, v0
	v_mov_b32_e32 v4, v0
	v_mov_b32_e32 v5, v0
	v_mov_b32_e32 v6, v0
	v_mov_b32_e32 v7, v0
	v_mov_b32_e32 v8, v0
	v_mov_b32_e32 v9, v0
	v_mov_b32_e32 v10, v0
	v_mov_b32_e32 v11, v0
	v_mov_b32_e32 v12, v0
	v_mov_b32_e32 v13, v0
	v_mov_b32_e32 v14, v0
	v_mov_b32_e32 v15, v0
	s_mov_b32 s0, 0x5002000
	s_waitcnt vmcnt(3)
	v_mfma_f32_32x32x16_bf16 v[32:47], v[64:67], v[114:117], v[0:15]
	s_waitcnt vmcnt(2)
	v_mfma_f32_32x32x16_bf16 v[32:47], v[68:71], v[118:121], v[32:47]
	s_waitcnt vmcnt(1)
	v_mfma_f32_32x32x16_bf16 v[32:47], v[72:75], v[122:125], v[32:47]
	v_mfma_f32_32x32x16_bf16 v[48:63], v[16:19], v[114:117], v[0:15]
	v_add_co_u32_e32 v16, vcc, s0, v80
	s_mov_b32 s0, 0x5003000
	s_nop 0
	v_addc_co_u32_e32 v17, vcc, 0, v81, vcc
	v_add_co_u32_e32 v18, vcc, s0, v80
	s_waitcnt vmcnt(0)
	v_mfma_f32_32x32x16_bf16 v[32:47], v[76:79], v[126:129], v[32:47]
	v_addc_co_u32_e32 v19, vcc, 0, v81, vcc
	global_load_dwordx4 v[64:67], v[18:19], off offset:-4096
	global_load_dwordx4 v[68:71], v[16:17], off offset:32
	global_load_dwordx4 v[72:75], v[16:17], off offset:64
	global_load_dwordx4 v[76:79], v[16:17], off offset:96
	global_load_dwordx4 v[80:83], v[18:19], off
	global_load_dwordx4 v[84:87], v[18:19], off offset:32
	global_load_dwordx4 v[88:91], v[18:19], off offset:64
	global_load_dwordx4 v[92:95], v[18:19], off offset:96
	v_mfma_f32_32x32x16_bf16 v[48:63], v[24:27], v[118:121], v[48:63]
	v_mfma_f32_32x32x16_bf16 v[48:63], v[20:23], v[122:125], v[48:63]
	v_mfma_f32_32x32x16_bf16 v[48:63], v[28:31], v[126:129], v[48:63]
	s_waitcnt vmcnt(7)
	v_mfma_f32_32x32x16_bf16 v[16:31], v[64:67], v[114:117], v[0:15]
	v_or_b32_e32 v164, s5, v167
	v_sub_u32_e32 v66, v164, v175
	v_subrev_u32_e32 v67, 31, v66
	v_writelane_b32 v253, s5, 2
	v_cmp_lt_i32_e32 vcc, -1, v67
	v_mov_b32_e32 v64, 0
	v_mov_b32_e32 v65, 0
	s_waitcnt vmcnt(3)
	v_mfma_f32_32x32x16_bf16 v[0:15], v[80:83], v[114:117], v[0:15]
	v_mfma_f32_32x32x16_bf16 v[16:31], v[68:71], v[118:121], v[16:31]
	s_waitcnt vmcnt(2)
	v_mfma_f32_32x32x16_bf16 v[0:15], v[84:87], v[118:121], v[0:15]
	v_mfma_f32_32x32x16_bf16 v[16:31], v[72:75], v[122:125], v[16:31]
	s_waitcnt vmcnt(1)
	v_mfma_f32_32x32x16_bf16 v[0:15], v[88:91], v[122:125], v[0:15]
	v_mfma_f32_32x32x16_bf16 v[16:31], v[76:79], v[126:129], v[16:31]
	s_waitcnt vmcnt(0)
	v_mfma_f32_32x32x16_bf16 v[0:15], v[92:95], v[126:129], v[0:15]
	v_add_u32_e32 v131, 0xffffffe1, v66
	v_min_u32_e32 v132, 0x7f, v131
	v_lshl_add_u32 v132, v132, 2, s33
	ds_read_b32 v132, v132
	v_ashrrev_i32_e32 v131, 31, v131
	v_add_u32_e32 v133, 0xffffffd1, v66
	v_min_u32_e32 v134, 0x7f, v133
	v_lshl_add_u32 v134, v134, 2, s33
	ds_read_b32 v134, v134
	v_ashrrev_i32_e32 v133, 31, v133
	v_add_u32_e32 v135, 0xffffffc1, v66
	v_min_u32_e32 v136, 0x7f, v135
	v_lshl_add_u32 v136, v136, 2, s33
	ds_read_b32 v136, v136
	v_ashrrev_i32_e32 v135, 31, v135
	v_add_u32_e32 v137, 0xffffffb1, v66
	v_min_u32_e32 v138, 0x7f, v137
	v_lshl_add_u32 v138, v138, 2, s33
	ds_read_b32 v138, v138
	v_ashrrev_i32_e32 v137, 31, v137
	v_add_u32_e32 v139, 0xffffff61, v66
	v_min_u32_e32 v140, 0x7f, v139
	v_lshl_add_u32 v140, v140, 2, s33
	ds_read_b32 v140, v140
	v_ashrrev_i32_e32 v139, 31, v139
	v_add_u32_e32 v141, 0xffffff51, v66
	v_min_u32_e32 v142, 0x7f, v141
	v_lshl_add_u32 v142, v142, 2, s33
	ds_read_b32 v142, v142
	v_ashrrev_i32_e32 v141, 31, v141
	v_add_u32_e32 v143, 0xffffff41, v66
	v_min_u32_e32 v144, 0x7f, v143
	v_lshl_add_u32 v144, v144, 2, s33
	ds_read_b32 v144, v144
	v_ashrrev_i32_e32 v143, 31, v143
	v_add_u32_e32 v145, 0xffffff31, v66
	v_min_u32_e32 v146, 0x7f, v145
	v_lshl_add_u32 v146, v146, 2, s33
	ds_read_b32 v146, v146
	v_ashrrev_i32_e32 v145, 31, v145
	v_add_u32_e32 v147, 0xfffffee1, v66
	v_min_u32_e32 v148, 0x7f, v147
	v_lshl_add_u32 v148, v148, 2, s33
	ds_read_b32 v148, v148
	v_ashrrev_i32_e32 v147, 31, v147
	v_add_u32_e32 v149, 0xfffffed1, v66
	v_min_u32_e32 v150, 0x7f, v149
	v_lshl_add_u32 v150, v150, 2, s33
	ds_read_b32 v150, v150
	v_ashrrev_i32_e32 v149, 31, v149
	v_add_u32_e32 v151, 0xfffffec1, v66
	v_min_u32_e32 v152, 0x7f, v151
	v_lshl_add_u32 v152, v152, 2, s33
	ds_read_b32 v152, v152
	v_ashrrev_i32_e32 v151, 31, v151
	v_add_u32_e32 v153, 0xfffffeb1, v66
	v_min_u32_e32 v154, 0x7f, v153
	v_lshl_add_u32 v154, v154, 2, s33
	ds_read_b32 v154, v154
	v_ashrrev_i32_e32 v153, 31, v153
	v_add_u32_e32 v155, 0xfffffe61, v66
	v_min_u32_e32 v156, 0x7f, v155
	v_lshl_add_u32 v156, v156, 2, s33
	ds_read_b32 v156, v156
	v_ashrrev_i32_e32 v155, 31, v155
	v_add_u32_e32 v157, 0xfffffe51, v66
	v_min_u32_e32 v158, 0x7f, v157
	v_lshl_add_u32 v158, v158, 2, s33
	ds_read_b32 v158, v158
	v_ashrrev_i32_e32 v157, 31, v157
	v_add_u32_e32 v159, 0xfffffe41, v66
	v_min_u32_e32 v160, 0x7f, v159
	v_lshl_add_u32 v160, v160, 2, s33
	ds_read_b32 v160, v160
	v_ashrrev_i32_e32 v159, 31, v159
	s_waitcnt lgkmcnt(14)
	v_add_f32_e32 v65, v48, v132
	v_exp_f32_e32 v65, v65
	s_nop 0
	v_bfi_b32 v65, v131, 0, v65
	v_add_u32_e32 v131, 0xfffffe31, v66
	v_min_u32_e32 v132, 0x7f, v131
	v_lshl_add_u32 v132, v132, 2, s33
	ds_read_b32 v132, v132
	v_ashrrev_i32_e32 v131, 31, v131
	s_waitcnt lgkmcnt(14)
	v_add_f32_e32 v64, v49, v134
	v_exp_f32_e32 v64, v64
	v_add_f32_e32 v161, 0, v65
	v_bfi_b32 v64, v133, 0, v64
	v_add_u32_e32 v133, 0xfffffde1, v66
	v_min_u32_e32 v134, 0x7f, v133
	v_lshl_add_u32 v134, v134, 2, s33
	ds_read_b32 v134, v134
	v_ashrrev_i32_e32 v133, 31, v133
	s_waitcnt lgkmcnt(14)
	v_add_f32_e32 v49, v50, v136
	v_exp_f32_e32 v49, v49
	v_add_f32_e32 v161, v161, v64
	v_bfi_b32 v49, v135, 0, v49
	v_add_u32_e32 v135, 0xfffffdd1, v66
	v_min_u32_e32 v136, 0x7f, v135
	v_lshl_add_u32 v136, v136, 2, s33
	ds_read_b32 v136, v136
	v_ashrrev_i32_e32 v135, 31, v135
	s_waitcnt lgkmcnt(14)
	v_add_f32_e32 v48, v51, v138
	v_exp_f32_e32 v48, v48
	v_add_f32_e32 v161, v161, v49
	v_bfi_b32 v48, v137, 0, v48
	v_add_u32_e32 v137, 0xfffffdc1, v66
	v_min_u32_e32 v138, 0x7f, v137
	v_lshl_add_u32 v138, v138, 2, s33
	ds_read_b32 v138, v138
	v_ashrrev_i32_e32 v137, 31, v137
	s_waitcnt lgkmcnt(14)
	v_add_f32_e32 v51, v52, v140
	v_exp_f32_e32 v51, v51
	v_add_f32_e32 v161, v161, v48
	v_bfi_b32 v51, v139, 0, v51
	v_add_u32_e32 v139, 0xfffffdb1, v66
	v_min_u32_e32 v140, 0x7f, v139
	v_lshl_add_u32 v140, v140, 2, s33
	ds_read_b32 v140, v140
	v_ashrrev_i32_e32 v139, 31, v139
	s_waitcnt lgkmcnt(14)
	v_add_f32_e32 v50, v53, v142
	v_exp_f32_e32 v50, v50
	v_add_f32_e32 v161, v161, v51
	v_bfi_b32 v50, v141, 0, v50
	v_add_u32_e32 v141, 0xfffffd61, v66
	v_min_u32_e32 v142, 0x7f, v141
	v_lshl_add_u32 v142, v142, 2, s33
	ds_read_b32 v142, v142
	v_ashrrev_i32_e32 v141, 31, v141
	s_waitcnt lgkmcnt(14)
	v_add_f32_e32 v53, v54, v144
	v_exp_f32_e32 v53, v53
	v_add_f32_e32 v161, v161, v50
	v_bfi_b32 v53, v143, 0, v53
	v_add_u32_e32 v143, 0xfffffd51, v66
	v_min_u32_e32 v144, 0x7f, v143
	v_lshl_add_u32 v144, v144, 2, s33
	ds_read_b32 v144, v144
	v_ashrrev_i32_e32 v143, 31, v143
	s_waitcnt lgkmcnt(14)
	v_add_f32_e32 v52, v55, v146
	v_exp_f32_e32 v52, v52
	v_add_f32_e32 v161, v161, v53
	v_bfi_b32 v52, v145, 0, v52
	v_add_u32_e32 v145, 0xfffffd41, v66
	v_min_u32_e32 v146, 0x7f, v145
	v_lshl_add_u32 v146, v146, 2, s33
	ds_read_b32 v146, v146
	v_ashrrev_i32_e32 v145, 31, v145
	s_waitcnt lgkmcnt(14)
	v_add_f32_e32 v55, v56, v148
	v_exp_f32_e32 v55, v55
	v_add_f32_e32 v161, v161, v52
	v_bfi_b32 v55, v147, 0, v55
	v_add_u32_e32 v147, 0xfffffd31, v66
	v_min_u32_e32 v148, 0x7f, v147
	v_lshl_add_u32 v148, v148, 2, s33
	ds_read_b32 v148, v148
	v_ashrrev_i32_e32 v147, 31, v147
	s_waitcnt lgkmcnt(14)
	v_add_f32_e32 v54, v57, v150
	v_exp_f32_e32 v54, v54
	v_add_f32_e32 v161, v161, v55
	v_bfi_b32 v54, v149, 0, v54
	v_add_u32_e32 v149, 0xfffffce1, v66
	v_min_u32_e32 v150, 0x7f, v149
	v_lshl_add_u32 v150, v150, 2, s33
	ds_read_b32 v150, v150
	v_ashrrev_i32_e32 v149, 31, v149
	s_waitcnt lgkmcnt(14)
	v_add_f32_e32 v57, v58, v152
	v_exp_f32_e32 v57, v57
	v_add_f32_e32 v161, v161, v54
	v_bfi_b32 v57, v151, 0, v57
	v_add_u32_e32 v151, 0xfffffcd1, v66
	v_min_u32_e32 v152, 0x7f, v151
	v_lshl_add_u32 v152, v152, 2, s33
	ds_read_b32 v152, v152
	v_ashrrev_i32_e32 v151, 31, v151
	s_waitcnt lgkmcnt(14)
	v_add_f32_e32 v56, v59, v154
	v_exp_f32_e32 v56, v56
	v_add_f32_e32 v161, v161, v57
	v_bfi_b32 v56, v153, 0, v56
	v_add_u32_e32 v153, 0xfffffcc1, v66
	v_min_u32_e32 v154, 0x7f, v153
	v_lshl_add_u32 v154, v154, 2, s33
	ds_read_b32 v154, v154
	v_ashrrev_i32_e32 v153, 31, v153
	s_waitcnt lgkmcnt(14)
	v_add_f32_e32 v59, v60, v156
	v_exp_f32_e32 v59, v59
	v_add_f32_e32 v161, v161, v56
	v_bfi_b32 v59, v155, 0, v59
	v_add_u32_e32 v155, 0xfffffcb1, v66
	v_min_u32_e32 v156, 0x7f, v155
	v_lshl_add_u32 v156, v156, 2, s33
	ds_read_b32 v156, v156
	v_ashrrev_i32_e32 v155, 31, v155
	s_waitcnt lgkmcnt(14)
	v_add_f32_e32 v58, v61, v158
	v_exp_f32_e32 v58, v58
	v_add_f32_e32 v161, v161, v59
	v_bfi_b32 v58, v157, 0, v58
	v_add_u32_e32 v157, 0xfffffc61, v66
	v_min_u32_e32 v158, 0x7f, v157
	v_lshl_add_u32 v158, v158, 2, s33
	ds_read_b32 v158, v158
	v_ashrrev_i32_e32 v157, 31, v157
	s_waitcnt lgkmcnt(14)
	v_add_f32_e32 v61, v62, v160
	v_exp_f32_e32 v61, v61
	v_add_f32_e32 v161, v161, v58
	v_bfi_b32 v61, v159, 0, v61
	v_add_u32_e32 v159, 0xfffffc51, v66
	v_min_u32_e32 v160, 0x7f, v159
	v_lshl_add_u32 v160, v160, 2, s33
	ds_read_b32 v160, v160
	v_ashrrev_i32_e32 v159, 31, v159
	s_waitcnt lgkmcnt(14)
	v_add_f32_e32 v60, v63, v132
	v_exp_f32_e32 v60, v60
	v_add_f32_e32 v161, v161, v61
	v_bfi_b32 v60, v131, 0, v60
	v_add_u32_e32 v131, 0xfffffc41, v66
	v_min_u32_e32 v132, 0x7f, v131
	v_lshl_add_u32 v132, v132, 2, s33
	ds_read_b32 v132, v132
	v_ashrrev_i32_e32 v131, 31, v131
	s_waitcnt lgkmcnt(14)
	v_add_f32_e32 v63, v32, v134
	v_exp_f32_e32 v63, v63
	v_add_f32_e32 v161, v161, v60
	v_bfi_b32 v63, v133, 0, v63
	v_add_u32_e32 v133, 0xfffffc31, v66
	v_min_u32_e32 v134, 0x7f, v133
	v_lshl_add_u32 v134, v134, 2, s33
	ds_read_b32 v134, v134
	v_ashrrev_i32_e32 v133, 31, v133
	s_waitcnt lgkmcnt(14)
	v_add_f32_e32 v62, v33, v136
	v_exp_f32_e32 v62, v62
	v_add_f32_e32 v161, v161, v63
	v_bfi_b32 v62, v135, 0, v62
	v_add_u32_e32 v135, 0xfffffbe1, v66
	v_min_u32_e32 v136, 0x7f, v135
	v_lshl_add_u32 v136, v136, 2, s33
	ds_read_b32 v136, v136
	v_ashrrev_i32_e32 v135, 31, v135
	s_waitcnt lgkmcnt(14)
	v_add_f32_e32 v33, v34, v138
	v_exp_f32_e32 v33, v33
	v_add_f32_e32 v161, v161, v62
	v_bfi_b32 v33, v137, 0, v33
	v_add_u32_e32 v137, 0xfffffbd1, v66
	v_min_u32_e32 v138, 0x7f, v137
	v_lshl_add_u32 v138, v138, 2, s33
	ds_read_b32 v138, v138
	v_ashrrev_i32_e32 v137, 31, v137
	s_waitcnt lgkmcnt(14)
	v_add_f32_e32 v32, v35, v140
	v_exp_f32_e32 v32, v32
	v_add_f32_e32 v161, v161, v33
	v_bfi_b32 v32, v139, 0, v32
	v_add_u32_e32 v139, 0xfffffbc1, v66
	v_min_u32_e32 v140, 0x7f, v139
	v_lshl_add_u32 v140, v140, 2, s33
	ds_read_b32 v140, v140
	v_ashrrev_i32_e32 v139, 31, v139
	s_waitcnt lgkmcnt(14)
	v_add_f32_e32 v35, v36, v142
	v_exp_f32_e32 v35, v35
	v_add_f32_e32 v161, v161, v32
	v_bfi_b32 v35, v141, 0, v35
	v_add_u32_e32 v141, 0xfffffbb1, v66
	v_min_u32_e32 v142, 0x7f, v141
	v_lshl_add_u32 v142, v142, 2, s33
	ds_read_b32 v142, v142
	v_ashrrev_i32_e32 v141, 31, v141
	s_waitcnt lgkmcnt(14)
	v_add_f32_e32 v34, v37, v144
	v_exp_f32_e32 v34, v34
	v_add_f32_e32 v161, v161, v35
	v_bfi_b32 v34, v143, 0, v34
	v_add_u32_e32 v143, 0xfffffb61, v66
	v_min_u32_e32 v144, 0x7f, v143
	v_lshl_add_u32 v144, v144, 2, s33
	ds_read_b32 v144, v144
	v_ashrrev_i32_e32 v143, 31, v143
	s_waitcnt lgkmcnt(14)
	v_add_f32_e32 v37, v38, v146
	v_exp_f32_e32 v37, v37
	v_add_f32_e32 v161, v161, v34
	v_bfi_b32 v37, v145, 0, v37
	v_add_u32_e32 v145, 0xfffffb51, v66
	v_min_u32_e32 v146, 0x7f, v145
	v_lshl_add_u32 v146, v146, 2, s33
	ds_read_b32 v146, v146
	v_ashrrev_i32_e32 v145, 31, v145
	s_waitcnt lgkmcnt(14)
	v_add_f32_e32 v36, v39, v148
	v_exp_f32_e32 v36, v36
	v_add_f32_e32 v161, v161, v37
	v_bfi_b32 v36, v147, 0, v36
	v_add_u32_e32 v147, 0xfffffb41, v66
	v_min_u32_e32 v148, 0x7f, v147
	v_lshl_add_u32 v148, v148, 2, s33
	ds_read_b32 v148, v148
	v_ashrrev_i32_e32 v147, 31, v147
	s_waitcnt lgkmcnt(14)
	v_add_f32_e32 v39, v40, v150
	v_exp_f32_e32 v39, v39
	v_add_f32_e32 v161, v161, v36
	v_bfi_b32 v39, v149, 0, v39
	v_add_u32_e32 v149, 0xfffffb31, v66
	v_min_u32_e32 v150, 0x7f, v149
	v_lshl_add_u32 v150, v150, 2, s33
	ds_read_b32 v150, v150
	v_ashrrev_i32_e32 v149, 31, v149
	s_waitcnt lgkmcnt(14)
	v_add_f32_e32 v38, v41, v152
	v_exp_f32_e32 v38, v38
	v_add_f32_e32 v161, v161, v39
	v_bfi_b32 v38, v151, 0, v38
	v_add_u32_e32 v151, 0xfffffae1, v66
	v_min_u32_e32 v152, 0x7f, v151
	v_lshl_add_u32 v152, v152, 2, s33
	ds_read_b32 v152, v152
	v_ashrrev_i32_e32 v151, 31, v151
	s_waitcnt lgkmcnt(14)
	v_add_f32_e32 v41, v42, v154
	v_exp_f32_e32 v41, v41
	v_add_f32_e32 v161, v161, v38
	v_bfi_b32 v41, v153, 0, v41
	v_add_u32_e32 v153, 0xfffffad1, v66
	v_min_u32_e32 v154, 0x7f, v153
	v_lshl_add_u32 v154, v154, 2, s33
	ds_read_b32 v154, v154
	v_ashrrev_i32_e32 v153, 31, v153
	s_waitcnt lgkmcnt(14)
	v_add_f32_e32 v40, v43, v156
	v_exp_f32_e32 v40, v40
	v_add_f32_e32 v161, v161, v41
	v_bfi_b32 v40, v155, 0, v40
	v_add_u32_e32 v155, 0xfffffac1, v66
	v_min_u32_e32 v156, 0x7f, v155
	v_lshl_add_u32 v156, v156, 2, s33
	ds_read_b32 v156, v156
	v_ashrrev_i32_e32 v155, 31, v155
	s_waitcnt lgkmcnt(14)
	v_add_f32_e32 v67, v44, v158
	v_exp_f32_e32 v67, v67
	v_add_f32_e32 v161, v161, v40
	v_bfi_b32 v67, v157, 0, v67
	v_add_u32_e32 v157, 0xfffffab1, v66
	v_min_u32_e32 v158, 0x7f, v157
	v_lshl_add_u32 v158, v158, 2, s33
	ds_read_b32 v158, v158
	v_ashrrev_i32_e32 v157, 31, v157
	s_waitcnt lgkmcnt(14)
	v_add_f32_e32 v43, v45, v160
	v_exp_f32_e32 v43, v43
	v_add_f32_e32 v161, v161, v67
	v_bfi_b32 v43, v159, 0, v43
	v_add_u32_e32 v159, 0xfffffa61, v66
	v_min_u32_e32 v160, 0x7f, v159
	v_lshl_add_u32 v160, v160, 2, s33
	ds_read_b32 v160, v160
	v_ashrrev_i32_e32 v159, 31, v159
	s_waitcnt lgkmcnt(14)
	v_add_f32_e32 v69, v46, v132
	v_exp_f32_e32 v69, v69
	v_add_f32_e32 v161, v161, v43
	v_bfi_b32 v69, v131, 0, v69
	v_add_u32_e32 v131, 0xfffffa51, v66
	v_min_u32_e32 v132, 0x7f, v131
	v_lshl_add_u32 v132, v132, 2, s33
	ds_read_b32 v132, v132
	v_ashrrev_i32_e32 v131, 31, v131
	s_waitcnt lgkmcnt(14)
	v_add_f32_e32 v68, v47, v134
	v_exp_f32_e32 v68, v68
	v_add_f32_e32 v161, v161, v69
	v_bfi_b32 v68, v133, 0, v68
	v_add_u32_e32 v133, 0xfffffa41, v66
	v_min_u32_e32 v134, 0x7f, v133
	v_lshl_add_u32 v134, v134, 2, s33
	ds_read_b32 v134, v134
	v_ashrrev_i32_e32 v133, 31, v133
	s_waitcnt lgkmcnt(14)
	v_add_f32_e32 v44, v16, v136
	v_exp_f32_e32 v44, v44
	v_add_f32_e32 v161, v161, v68
	v_bfi_b32 v44, v135, 0, v44
	v_add_u32_e32 v135, 0xfffffa31, v66
	v_min_u32_e32 v136, 0x7f, v135
	v_lshl_add_u32 v136, v136, 2, s33
	ds_read_b32 v136, v136
	v_ashrrev_i32_e32 v135, 31, v135
	s_waitcnt lgkmcnt(14)
	v_add_f32_e32 v42, v17, v138
	v_exp_f32_e32 v42, v42
	v_add_f32_e32 v161, v161, v44
	v_bfi_b32 v42, v137, 0, v42
	v_add_u32_e32 v137, 0xfffff9e1, v66
	v_min_u32_e32 v138, 0x7f, v137
	v_lshl_add_u32 v138, v138, 2, s33
	ds_read_b32 v138, v138
	v_ashrrev_i32_e32 v137, 31, v137
	s_waitcnt lgkmcnt(14)
	v_add_f32_e32 v46, v18, v140
	v_exp_f32_e32 v46, v46
	v_add_f32_e32 v161, v161, v42
	v_bfi_b32 v46, v139, 0, v46
	v_add_u32_e32 v139, 0xfffff9d1, v66
	v_min_u32_e32 v140, 0x7f, v139
	v_lshl_add_u32 v140, v140, 2, s33
	ds_read_b32 v140, v140
	v_ashrrev_i32_e32 v139, 31, v139
	s_waitcnt lgkmcnt(14)
	v_add_f32_e32 v45, v19, v142
	v_exp_f32_e32 v45, v45
	v_add_f32_e32 v161, v161, v46
	v_bfi_b32 v45, v141, 0, v45
	v_add_u32_e32 v141, 0xfffff9c1, v66
	v_min_u32_e32 v142, 0x7f, v141
	v_lshl_add_u32 v142, v142, 2, s33
	ds_read_b32 v142, v142
	v_ashrrev_i32_e32 v141, 31, v141
	s_waitcnt lgkmcnt(14)
	v_add_f32_e32 v70, v20, v144
	v_exp_f32_e32 v70, v70
	v_add_f32_e32 v161, v161, v45
	v_bfi_b32 v70, v143, 0, v70
	v_add_u32_e32 v143, 0xfffff9b1, v66
	v_min_u32_e32 v144, 0x7f, v143
	v_lshl_add_u32 v144, v144, 2, s33
	ds_read_b32 v144, v144
	v_ashrrev_i32_e32 v143, 31, v143
	s_waitcnt lgkmcnt(14)
	v_add_f32_e32 v47, v21, v146
	v_exp_f32_e32 v47, v47
	v_add_f32_e32 v161, v161, v70
	v_bfi_b32 v47, v145, 0, v47
	v_add_u32_e32 v145, 0xfffff961, v66
	v_min_u32_e32 v146, 0x7f, v145
	v_lshl_add_u32 v146, v146, 2, s33
	ds_read_b32 v146, v146
	v_ashrrev_i32_e32 v145, 31, v145
	s_waitcnt lgkmcnt(14)
	v_add_f32_e32 v72, v22, v148
	v_exp_f32_e32 v72, v72
	v_add_f32_e32 v161, v161, v47
	v_bfi_b32 v72, v147, 0, v72
	v_add_u32_e32 v147, 0xfffff951, v66
	v_min_u32_e32 v148, 0x7f, v147
	v_lshl_add_u32 v148, v148, 2, s33
	ds_read_b32 v148, v148
	v_ashrrev_i32_e32 v147, 31, v147
	s_waitcnt lgkmcnt(14)
	v_add_f32_e32 v71, v23, v150
	v_exp_f32_e32 v71, v71
	v_add_f32_e32 v161, v161, v72
	v_bfi_b32 v71, v149, 0, v71
	v_add_u32_e32 v149, 0xfffff941, v66
	v_min_u32_e32 v150, 0x7f, v149
	v_lshl_add_u32 v150, v150, 2, s33
	ds_read_b32 v150, v150
	v_ashrrev_i32_e32 v149, 31, v149
	s_waitcnt lgkmcnt(14)
	v_add_f32_e32 v74, v24, v152
	v_exp_f32_e32 v74, v74
	v_add_f32_e32 v161, v161, v71
	v_bfi_b32 v74, v151, 0, v74
	v_add_u32_e32 v151, 0xfffff931, v66
	v_min_u32_e32 v152, 0x7f, v151
	v_lshl_add_u32 v152, v152, 2, s33
	ds_read_b32 v152, v152
	v_ashrrev_i32_e32 v151, 31, v151
	s_waitcnt lgkmcnt(14)
	v_add_f32_e32 v73, v25, v154
	v_exp_f32_e32 v73, v73
	v_add_f32_e32 v161, v161, v74
	v_bfi_b32 v73, v153, 0, v73
	v_add_u32_e32 v153, 0xfffff8e1, v66
	v_min_u32_e32 v154, 0x7f, v153
	v_lshl_add_u32 v154, v154, 2, s33
	ds_read_b32 v154, v154
	v_ashrrev_i32_e32 v153, 31, v153
	s_waitcnt lgkmcnt(14)
	v_add_f32_e32 v76, v26, v156
	v_exp_f32_e32 v76, v76
	v_add_f32_e32 v161, v161, v73
	v_bfi_b32 v76, v155, 0, v76
	v_add_u32_e32 v155, 0xfffff8d1, v66
	v_min_u32_e32 v156, 0x7f, v155
	v_lshl_add_u32 v156, v156, 2, s33
	ds_read_b32 v156, v156
	v_ashrrev_i32_e32 v155, 31, v155
	s_waitcnt lgkmcnt(14)
	v_add_f32_e32 v75, v27, v158
	v_exp_f32_e32 v75, v75
	v_add_f32_e32 v161, v161, v76
	v_bfi_b32 v75, v157, 0, v75
	v_add_u32_e32 v157, 0xfffff8c1, v66
	v_min_u32_e32 v158, 0x7f, v157
	v_lshl_add_u32 v158, v158, 2, s33
	ds_read_b32 v158, v158
	v_ashrrev_i32_e32 v157, 31, v157
	s_waitcnt lgkmcnt(14)
	v_add_f32_e32 v78, v28, v160
	v_exp_f32_e32 v78, v78
	v_add_f32_e32 v161, v161, v75
	v_bfi_b32 v78, v159, 0, v78
	v_add_u32_e32 v159, 0xfffff8b1, v66
	v_min_u32_e32 v160, 0x7f, v159
	v_lshl_add_u32 v160, v160, 2, s33
	ds_read_b32 v160, v160
	v_ashrrev_i32_e32 v159, 31, v159
	s_waitcnt lgkmcnt(14)
	v_add_f32_e32 v77, v29, v132
	v_exp_f32_e32 v77, v77
	v_add_f32_e32 v161, v161, v78
	v_bfi_b32 v77, v131, 0, v77
	v_add_u32_e32 v131, 0xfffff861, v66
	v_min_u32_e32 v132, 0x7f, v131
	v_lshl_add_u32 v132, v132, 2, s33
	ds_read_b32 v132, v132
	v_ashrrev_i32_e32 v131, 31, v131
	s_waitcnt lgkmcnt(14)
	v_add_f32_e32 v80, v30, v134
	v_exp_f32_e32 v80, v80
	v_add_f32_e32 v161, v161, v77
	v_bfi_b32 v80, v133, 0, v80
	v_add_u32_e32 v133, 0xfffff851, v66
	v_min_u32_e32 v134, 0x7f, v133
	v_lshl_add_u32 v134, v134, 2, s33
	ds_read_b32 v134, v134
	v_ashrrev_i32_e32 v133, 31, v133
	s_waitcnt lgkmcnt(14)
	v_add_f32_e32 v79, v31, v136
	v_exp_f32_e32 v79, v79
	v_add_f32_e32 v161, v161, v80
	v_bfi_b32 v79, v135, 0, v79
	v_add_u32_e32 v135, 0xfffff841, v66
	v_min_u32_e32 v136, 0x7f, v135
	v_lshl_add_u32 v136, v136, 2, s33
	ds_read_b32 v136, v136
	v_ashrrev_i32_e32 v135, 31, v135
	s_waitcnt lgkmcnt(14)
	v_add_f32_e32 v82, v0, v138
	v_exp_f32_e32 v82, v82
	v_add_f32_e32 v161, v161, v79
	v_bfi_b32 v82, v137, 0, v82
	v_add_u32_e32 v137, 0xfffff831, v66
	v_min_u32_e32 v138, 0x7f, v137
	v_lshl_add_u32 v138, v138, 2, s33
	ds_read_b32 v138, v138
	v_ashrrev_i32_e32 v137, 31, v137
	s_waitcnt lgkmcnt(14)
	v_add_f32_e32 v81, v1, v140
	v_exp_f32_e32 v81, v81
	v_add_f32_e32 v161, v161, v82
	v_bfi_b32 v81, v139, 0, v81
	s_waitcnt lgkmcnt(13)
	v_add_f32_e32 v84, v2, v142
	v_exp_f32_e32 v84, v84
	v_add_f32_e32 v161, v161, v81
	v_bfi_b32 v84, v141, 0, v84
	s_waitcnt lgkmcnt(12)
	v_add_f32_e32 v83, v3, v144
	v_exp_f32_e32 v83, v83
	v_add_f32_e32 v161, v161, v84
	v_bfi_b32 v83, v143, 0, v83
	s_waitcnt lgkmcnt(11)
	v_add_f32_e32 v86, v4, v146
	v_exp_f32_e32 v86, v86
	v_add_f32_e32 v161, v161, v83
	v_bfi_b32 v86, v145, 0, v86
	s_waitcnt lgkmcnt(10)
	v_add_f32_e32 v85, v5, v148
	v_exp_f32_e32 v85, v85
	v_add_f32_e32 v161, v161, v86
	v_bfi_b32 v85, v147, 0, v85
	s_waitcnt lgkmcnt(9)
	v_add_f32_e32 v88, v6, v150
	v_exp_f32_e32 v88, v88
	v_add_f32_e32 v161, v161, v85
	v_bfi_b32 v88, v149, 0, v88
	s_waitcnt lgkmcnt(8)
	v_add_f32_e32 v87, v7, v152
	v_exp_f32_e32 v87, v87
	v_add_f32_e32 v161, v161, v88
	v_bfi_b32 v87, v151, 0, v87
	s_waitcnt lgkmcnt(7)
	v_add_f32_e32 v90, v8, v154
	v_exp_f32_e32 v90, v90
	v_add_f32_e32 v161, v161, v87
	v_bfi_b32 v90, v153, 0, v90
	s_waitcnt lgkmcnt(6)
	v_add_f32_e32 v89, v9, v156
	v_exp_f32_e32 v89, v89
	v_add_f32_e32 v161, v161, v90
	v_bfi_b32 v89, v155, 0, v89
	s_waitcnt lgkmcnt(5)
	v_add_f32_e32 v92, v10, v158
	v_exp_f32_e32 v92, v92
	v_add_f32_e32 v161, v161, v89
	v_bfi_b32 v92, v157, 0, v92
	s_waitcnt lgkmcnt(4)
	v_add_f32_e32 v91, v11, v160
	v_exp_f32_e32 v91, v91
	v_add_f32_e32 v161, v161, v92
	v_bfi_b32 v91, v159, 0, v91
	s_waitcnt lgkmcnt(3)
	v_add_f32_e32 v94, v12, v132
	v_exp_f32_e32 v94, v94
	v_add_f32_e32 v161, v161, v91
	v_bfi_b32 v94, v131, 0, v94
	s_waitcnt lgkmcnt(2)
	v_add_f32_e32 v93, v13, v134
	v_exp_f32_e32 v93, v93
	v_add_f32_e32 v161, v161, v94
	v_bfi_b32 v93, v133, 0, v93
	s_waitcnt lgkmcnt(1)
	v_add_f32_e32 v130, v14, v136
	v_exp_f32_e32 v130, v130
	v_add_f32_e32 v161, v161, v93
	v_bfi_b32 v130, v135, 0, v130
	s_waitcnt lgkmcnt(0)
	v_add_f32_e32 v95, v15, v138
	v_exp_f32_e32 v95, v95
	v_add_f32_e32 v161, v161, v130
	v_bfi_b32 v95, v137, 0, v95
	v_add_f32_e32 v0, v161, v95
	v_readlane_b32 s0, v253, 1
	s_lshl_b32 s2, s0, 13
	ds_bpermute_b32 v1, v163, v0
	v_mul_f32_e32 v2, 0.5, v48
	ds_bpermute_b32 v2, v163, v2
	v_readlane_b32 s4, v251, 42
	v_readlane_b32 s5, v251, 43
	s_waitcnt lgkmcnt(1)
	v_add_f32_e32 v0, v0, v1
	v_div_scale_f32 v1, s[0:1], v0, v0, 1.0
	v_rcp_f32_e32 v3, v1
	v_div_scale_f32 v4, vcc, 1.0, v0, 1.0
	s_lshl_b32 s0, s2, 1
	v_fma_f32 v5, -v1, v3, 1.0
	v_fmac_f32_e32 v3, v5, v3
	v_mul_f32_e32 v5, v4, v3
	v_fma_f32 v6, -v1, v5, v4
	v_fmac_f32_e32 v5, v6, v3
	v_fma_f32 v1, -v1, v5, v4
	v_div_fmas_f32 v1, v1, v3, v5
	v_div_fixup_f32 v1, v1, v0, 1.0
	v_cmp_lt_f32_e32 vcc, 0, v0
	v_add_f32_e32 v0, v65, v64
	v_add_f32_e32 v3, v51, v50
	v_cndmask_b32_e32 v66, 0, v1, vcc
	v_fma_f32 v1, 0.5, v48, v49
	v_add_f32_e32 v0, v0, v1
	s_waitcnt lgkmcnt(0)
	v_cndmask_b32_e64 v1, v2, 0, s[4:5]
	v_add_f32_e32 v0, v0, v1
	v_mul_f32_e32 v1, 0.5, v52
	ds_bpermute_b32 v1, v163, v1
	v_fma_f32 v4, 0.5, v52, v53
	v_add_f32_e32 v3, v3, v4
	v_mul_f32_e32 v0, v66, v0
	v_fma_f32 v4, 0.5, v60, v61
	s_waitcnt lgkmcnt(0)
	v_cndmask_b32_e64 v2, v1, v2, s[4:5]
	v_add_f32_e32 v2, v3, v2
	v_mul_f32_e32 v3, 0.5, v56
	ds_bpermute_b32 v3, v163, v3
	v_mul_f32_e32 v2, v66, v2
	ds_write2_b32 v239, v0, v2 offset1:2
	v_add_f32_e32 v0, v55, v54
	v_fma_f32 v2, 0.5, v56, v57
	v_add_f32_e32 v0, v0, v2
	s_waitcnt lgkmcnt(1)
	v_cndmask_b32_e64 v1, v3, v1, s[4:5]
	v_add_f32_e32 v0, v0, v1
	v_mul_f32_e32 v1, 0.5, v60
	ds_bpermute_b32 v1, v163, v1
	v_add_f32_e32 v2, v59, v58
	v_add_f32_e32 v2, v2, v4
	v_mul_f32_e32 v0, v66, v0
	v_fma_f32 v4, 0.5, v36, v37
	s_waitcnt lgkmcnt(0)
	v_cndmask_b32_e64 v3, v1, v3, s[4:5]
	v_add_f32_e32 v2, v2, v3
	v_mul_f32_e32 v3, 0.5, v32
	ds_bpermute_b32 v3, v163, v3
	v_mul_f32_e32 v2, v66, v2
	ds_write2_b32 v239, v0, v2 offset0:4 offset1:6
	v_add_f32_e32 v0, v63, v62
	v_fma_f32 v2, 0.5, v32, v33
	v_add_f32_e32 v0, v0, v2
	s_waitcnt lgkmcnt(1)
	v_cndmask_b32_e64 v1, v3, v1, s[4:5]
	v_add_f32_e32 v0, v0, v1
	v_mul_f32_e32 v1, 0.5, v36
	ds_bpermute_b32 v1, v163, v1
	v_add_f32_e32 v2, v35, v34
	v_add_f32_e32 v2, v2, v4
	v_readlane_b32 s2, v252, 62
	v_mul_f32_e32 v0, v66, v0
	s_waitcnt lgkmcnt(0)
	v_cndmask_b32_e64 v3, v1, v3, s[4:5]
	v_add_f32_e32 v2, v2, v3
	v_mul_f32_e32 v3, 0.5, v40
	ds_bpermute_b32 v4, v163, v3
	v_mul_f32_e32 v2, v66, v2
	v_readlane_b32 s3, v252, 63
	s_add_u32 s0, s2, s0
	ds_write2_b32 v239, v0, v2 offset0:8 offset1:10
	v_add_f32_e32 v0, v39, v38
	v_fma_f32 v2, 0.5, v40, v41
	s_addc_u32 s1, s3, 0
	v_mov_b32_e32 v189, v97
	v_add_f32_e32 v5, v0, v2
	s_waitcnt lgkmcnt(1)
	v_cndmask_b32_e64 v6, v4, v1, s[4:5]
	v_lshl_add_u64 v[0:1], s[0:1], 0, v[188:189]
	s_mov_b64 s[0:1], 0x5200000
	v_lshl_add_u64 v[0:1], v[0:1], 0, s[0:1]
	v_mov_b32_e32 v191, v97
	v_lshl_add_u64 v[156:157], v[0:1], 0, v[190:191]
	v_mov_b32_e32 v193, v97
	v_lshl_add_u64 v[158:159], v[0:1], 0, v[192:193]
	global_load_dwordx2 v[0:1], v[156:157], off
	global_load_dwordx2 v[2:3], v[156:157], off offset:16
	global_load_dwordx2 v[132:133], v[156:157], off offset:32
	global_load_dwordx2 v[134:135], v[156:157], off offset:48
	global_load_dwordx2 v[16:17], v[158:159], off
	global_load_dwordx2 v[18:19], v[158:159], off offset:16
	global_load_dwordx2 v[136:137], v[158:159], off offset:32
	global_load_dwordx2 v[138:139], v[158:159], off offset:48
	global_load_dwordx2 v[140:141], v[156:157], off offset:64
	global_load_dwordx2 v[142:143], v[156:157], off offset:80
	global_load_dwordx2 v[144:145], v[156:157], off offset:96
	global_load_dwordx2 v[146:147], v[156:157], off offset:112
	global_load_dwordx2 v[148:149], v[158:159], off offset:64
	global_load_dwordx2 v[150:151], v[158:159], off offset:80
	global_load_dwordx2 v[152:153], v[158:159], off offset:96
	global_load_dwordx2 v[154:155], v[158:159], off offset:112
	v_add_f32_e32 v5, v5, v6
	v_mul_f32_e32 v6, 0.5, v68
	ds_bpermute_b32 v6, v163, v6
	v_add_f32_e32 v7, v67, v43
	v_fma_f32 v8, 0.5, v68, v69
	v_add_f32_e32 v7, v7, v8
	v_mul_f32_e32 v5, v66, v5
	s_waitcnt lgkmcnt(0)
	v_cndmask_b32_e64 v4, v6, v4, s[4:5]
	v_add_f32_e32 v4, v7, v4
	v_mul_f32_e32 v7, 0.5, v45
	ds_bpermute_b32 v7, v163, v7
	v_mul_f32_e32 v4, v66, v4
	ds_write2_b32 v239, v5, v4 offset0:12 offset1:14
	v_add_f32_e32 v4, v44, v42
	v_fma_f32 v5, 0.5, v45, v46
	v_add_f32_e32 v4, v4, v5
	s_waitcnt lgkmcnt(1)
	v_cndmask_b32_e64 v5, v7, v6, s[4:5]
	v_add_f32_e32 v4, v4, v5
	v_mul_f32_e32 v5, 0.5, v71
	ds_bpermute_b32 v5, v163, v5
	v_add_f32_e32 v6, v70, v47
	v_fma_f32 v8, 0.5, v71, v72
	v_add_f32_e32 v6, v6, v8
	v_mul_f32_e32 v4, v66, v4
	s_waitcnt lgkmcnt(0)
	v_cndmask_b32_e64 v7, v5, v7, s[4:5]
	v_add_f32_e32 v6, v6, v7
	v_mul_f32_e32 v7, 0.5, v75
	ds_bpermute_b32 v7, v163, v7
	v_mul_f32_e32 v6, v66, v6
	ds_write2_b32 v239, v4, v6 offset0:16 offset1:18
	v_add_f32_e32 v4, v74, v73
	v_fma_f32 v6, 0.5, v75, v76
	v_add_f32_e32 v4, v4, v6
	s_waitcnt lgkmcnt(1)
	v_cndmask_b32_e64 v5, v7, v5, s[4:5]
	v_add_f32_e32 v4, v4, v5
	v_mul_f32_e32 v5, 0.5, v79
	ds_bpermute_b32 v5, v163, v5
	v_add_f32_e32 v6, v78, v77
	v_fma_f32 v8, 0.5, v79, v80
	v_add_f32_e32 v6, v6, v8
	v_mul_f32_e32 v4, v66, v4
	s_waitcnt lgkmcnt(0)
	v_cndmask_b32_e64 v7, v5, v7, s[4:5]
	v_add_f32_e32 v6, v6, v7
	v_mul_f32_e32 v7, 0.5, v83
	ds_bpermute_b32 v7, v163, v7
	v_mul_f32_e32 v6, v66, v6
	ds_write2_b32 v239, v4, v6 offset0:20 offset1:22
	v_add_f32_e32 v4, v82, v81
	v_fma_f32 v6, 0.5, v83, v84
	v_add_f32_e32 v4, v4, v6
	s_waitcnt lgkmcnt(1)
	v_cndmask_b32_e64 v5, v7, v5, s[4:5]
	v_add_f32_e32 v4, v4, v5
	v_mul_f32_e32 v5, 0.5, v87
	ds_bpermute_b32 v5, v163, v5
	v_add_f32_e32 v6, v86, v85
	v_fma_f32 v8, 0.5, v87, v88
	v_add_f32_e32 v6, v6, v8
	v_mul_f32_e32 v4, v66, v4
	s_waitcnt lgkmcnt(0)
	v_cndmask_b32_e64 v7, v5, v7, s[4:5]
	v_add_f32_e32 v6, v6, v7
	v_mul_f32_e32 v7, 0.5, v91
	ds_bpermute_b32 v7, v163, v7
	v_mul_f32_e32 v6, v66, v6
	ds_write2_b32 v239, v4, v6 offset0:24 offset1:26
	v_add_f32_e32 v4, v90, v89
	v_fma_f32 v6, 0.5, v91, v92
	v_add_f32_e32 v4, v4, v6
	s_waitcnt lgkmcnt(1)
	v_cndmask_b32_e64 v5, v7, v5, s[4:5]
	v_add_f32_e32 v4, v4, v5
	v_mul_f32_e32 v5, 0.5, v95
	ds_bpermute_b32 v5, v163, v5
	v_add_f32_e32 v6, v94, v93
	v_fma_f32 v8, 0.5, v95, v130
	v_add_f32_e32 v6, v6, v8
	v_mul_f32_e32 v4, v66, v4
	s_waitcnt lgkmcnt(0)
	v_cndmask_b32_e64 v5, v5, v7, s[4:5]
	v_add_f32_e32 v5, v6, v5
	v_mul_f32_e32 v5, v66, v5
	ds_write2_b32 v239, v4, v5 offset0:28 offset1:30
	v_cvt_pk_bf16_f32 v20, v65, v64
	v_cvt_pk_bf16_f32 v21, v49, v48
	v_cvt_pk_bf16_f32 v22, v51, v50
	v_cvt_pk_bf16_f32 v23, v53, v52
	v_cvt_pk_bf16_f32 v48, v55, v54
	v_cvt_pk_bf16_f32 v49, v57, v56
	s_waitcnt vmcnt(14)
	v_mfma_f32_32x32x16_bf16 v[0:15], v[0:3], v[20:23], 0
	v_cvt_pk_bf16_f32 v50, v59, v58
	v_cvt_pk_bf16_f32 v51, v61, v60
	s_waitcnt vmcnt(10)
	v_mfma_f32_32x32x16_bf16 v[16:31], v[16:19], v[20:23], 0
	v_mfma_f32_32x32x16_bf16 v[0:15], v[132:135], v[48:51], v[0:15]
	s_waitcnt vmcnt(8)
	v_mfma_f32_32x32x16_bf16 v[16:31], v[136:139], v[48:51], v[16:31]
	v_cvt_pk_bf16_f32 v48, v63, v62
	v_cvt_pk_bf16_f32 v49, v33, v32
	v_cvt_pk_bf16_f32 v50, v35, v34
	v_cvt_pk_bf16_f32 v51, v37, v36
	v_cvt_pk_bf16_f32 v32, v39, v38
	v_cvt_pk_bf16_f32 v33, v41, v40
	v_cvt_pk_bf16_f32 v34, v67, v43
	s_waitcnt vmcnt(6)
	v_mfma_f32_32x32x16_bf16 v[0:15], v[140:143], v[48:51], v[0:15]
	v_cvt_pk_bf16_f32 v35, v69, v68
	s_waitcnt vmcnt(2)
	v_mfma_f32_32x32x16_bf16 v[16:31], v[148:151], v[48:51], v[16:31]
	v_mfma_f32_32x32x16_bf16 v[0:15], v[144:147], v[32:35], v[0:15]
	s_waitcnt vmcnt(0)
	v_mfma_f32_32x32x16_bf16 v[16:31], v[152:155], v[32:35], v[16:31]
	global_load_dwordx2 v[32:33], v[156:157], off offset:128
	global_load_dwordx2 v[34:35], v[156:157], off offset:144
	global_load_dwordx2 v[36:37], v[158:159], off offset:128
	global_load_dwordx2 v[38:39], v[158:159], off offset:144
	global_load_dwordx2 v[48:49], v[156:157], off offset:160
	global_load_dwordx2 v[50:51], v[156:157], off offset:176
	global_load_dwordx2 v[52:53], v[158:159], off offset:160
	global_load_dwordx2 v[54:55], v[158:159], off offset:176
	global_load_dwordx2 v[56:57], v[156:157], off offset:192
	global_load_dwordx2 v[58:59], v[156:157], off offset:208
	global_load_dwordx2 v[60:61], v[158:159], off offset:192
	global_load_dwordx2 v[62:63], v[158:159], off offset:208
	global_load_dwordx2 v[132:133], v[156:157], off offset:224
	global_load_dwordx2 v[134:135], v[156:157], off offset:240
	global_load_dwordx2 v[136:137], v[158:159], off offset:224
	global_load_dwordx2 v[138:139], v[158:159], off offset:240
	v_cvt_pk_bf16_f32 v40, v44, v42
	v_cvt_pk_bf16_f32 v41, v46, v45
	v_cvt_pk_bf16_f32 v42, v70, v47
	v_cvt_pk_bf16_f32 v43, v72, v71
	v_readlane_b32 s0, v251, 44
	v_readlane_b32 s1, v251, 45
	s_waitcnt vmcnt(14)
	v_mfma_f32_32x32x16_bf16 v[0:15], v[32:35], v[40:43], v[0:15]
	v_cvt_pk_bf16_f32 v32, v74, v73
	v_cvt_pk_bf16_f32 v33, v76, v75
	v_cvt_pk_bf16_f32 v34, v78, v77
	v_cvt_pk_bf16_f32 v35, v80, v79
	s_mov_b64 s[14:15], -1
	s_mov_b64 s[12:13], -1
	s_waitcnt vmcnt(12)
	v_mfma_f32_32x32x16_bf16 v[16:31], v[36:39], v[40:43], v[16:31]
	s_waitcnt vmcnt(10)
	v_mfma_f32_32x32x16_bf16 v[0:15], v[48:51], v[32:35], v[0:15]
	s_waitcnt vmcnt(8)
	v_mfma_f32_32x32x16_bf16 v[16:31], v[52:55], v[32:35], v[16:31]
	v_cvt_pk_bf16_f32 v32, v82, v81
	v_cvt_pk_bf16_f32 v33, v84, v83
	v_cvt_pk_bf16_f32 v34, v86, v85
	v_cvt_pk_bf16_f32 v35, v88, v87
	s_waitcnt vmcnt(6)
	s_nop 0
	v_mfma_f32_32x32x16_bf16 v[0:15], v[56:59], v[32:35], v[0:15]
	s_waitcnt vmcnt(4)
	v_mfma_f32_32x32x16_bf16 v[16:31], v[60:63], v[32:35], v[16:31]
	v_cvt_pk_bf16_f32 v32, v90, v89
	v_cvt_pk_bf16_f32 v33, v92, v91
	v_cvt_pk_bf16_f32 v34, v94, v93
	v_cvt_pk_bf16_f32 v35, v130, v95
	s_waitcnt vmcnt(2)
	s_nop 0
	v_mfma_f32_32x32x16_bf16 v[0:15], v[132:135], v[32:35], v[0:15]
	s_waitcnt vmcnt(0)
	v_mfma_f32_32x32x16_bf16 v[16:31], v[136:139], v[32:35], v[16:31]
	v_mul_f32_e32 v32, v162, v66
	s_nop 8
	v_mul_f32_e32 v0, v32, v0
	v_mul_f32_e32 v1, v32, v1
	ds_write2st64_b32 v173, v0, v1 offset1:1
	v_mul_f32_e32 v16, v32, v16
	v_mul_f32_e32 v0, v32, v17
	ds_write2st64_b32 v173, v16, v0 offset0:16 offset1:17
	v_mul_f32_e32 v0, v32, v2
	v_mul_f32_e32 v2, v32, v3
	v_mul_f32_e32 v1, v32, v18
	ds_write2st64_b32 v173, v0, v2 offset0:2 offset1:3
	v_mul_f32_e32 v0, v32, v19
	ds_write2st64_b32 v173, v1, v0 offset0:18 offset1:19
	v_mul_f32_e32 v0, v32, v4
	v_mul_f32_e32 v2, v32, v5
	v_mul_f32_e32 v1, v32, v20
	ds_write2st64_b32 v173, v0, v2 offset0:4 offset1:5
	v_mul_f32_e32 v0, v32, v21
	ds_write2st64_b32 v173, v1, v0 offset0:20 offset1:21
	v_mul_f32_e32 v0, v32, v6
	v_mul_f32_e32 v2, v32, v7
	v_mul_f32_e32 v1, v32, v22
	ds_write2st64_b32 v173, v0, v2 offset0:6 offset1:7
	v_mul_f32_e32 v0, v32, v23
	ds_write2st64_b32 v173, v1, v0 offset0:22 offset1:23
	v_mul_f32_e32 v0, v32, v8
	v_mul_f32_e32 v2, v32, v9
	v_mul_f32_e32 v1, v32, v24
	ds_write2st64_b32 v173, v0, v2 offset0:8 offset1:9
	v_mul_f32_e32 v0, v32, v25
	ds_write2st64_b32 v173, v1, v0 offset0:24 offset1:25
	v_mul_f32_e32 v0, v32, v10
	v_mul_f32_e32 v2, v32, v11
	v_mul_f32_e32 v1, v32, v26
	ds_write2st64_b32 v173, v0, v2 offset0:10 offset1:11
	v_mul_f32_e32 v0, v32, v27
	ds_write2st64_b32 v173, v1, v0 offset0:26 offset1:27
	v_mul_f32_e32 v0, v32, v12
	v_mul_f32_e32 v2, v32, v13
	v_mul_f32_e32 v1, v32, v28
	ds_write2st64_b32 v173, v0, v2 offset0:12 offset1:13
	v_mul_f32_e32 v0, v32, v29
	ds_write2st64_b32 v173, v1, v0 offset0:28 offset1:29
	v_mul_f32_e32 v0, v32, v14
	v_mul_f32_e32 v2, v32, v15
	v_mul_f32_e32 v1, v32, v30
	ds_write2st64_b32 v173, v0, v2 offset0:14 offset1:15
	v_mul_f32_e32 v0, v32, v31
	ds_write2st64_b32 v173, v1, v0 offset0:30 offset1:31
	s_waitcnt lgkmcnt(0)
	s_barrier
	s_add_i32 s51, s50, -2
	s_lshl_b32 s16, 1, s50
	s_lshr_b32 s17, s16, 1
	s_or_b32 s16, s16, s17
	s_or_b32 s16, s16, 1
	s_bcnt1_i32_b32 s17, s16
	s_sub_i32 s17, 8, s17
	s_max_i32 s18, s51, 0
	v_lshl_add_u32 v134, v177, 2, v240
	ds_read_b128 v[80:83], v134
	ds_read_b128 v[84:87], v134 offset:9216
	ds_read_b128 v[88:91], v134 offset:18432
	ds_read_b128 v[92:95], v134 offset:27648
	ds_read_b128 v[32:35], v240
	ds_read_b128 v[36:39], v240 offset:9216
	ds_read_b128 v[40:43], v240 offset:18432
	ds_read_b128 v[44:47], v240 offset:27648
	ds_read_b128 v[48:51], v240 offset:16
	ds_read_b128 v[52:55], v240 offset:9232
	ds_read_b128 v[56:59], v240 offset:18448
	ds_read_b128 v[60:63], v240 offset:27664
	s_waitcnt lgkmcnt(8)
	v_pk_add_f32 v[80:81], v[80:81], v[84:85]
	v_pk_add_f32 v[82:83], v[82:83], v[86:87]
	v_pk_add_f32 v[88:89], v[88:89], v[92:93]
	v_pk_add_f32 v[90:91], v[90:91], v[94:95]
	v_pk_add_f32 v[80:81], v[80:81], v[88:89]
	v_pk_add_f32 v[82:83], v[82:83], v[90:91]
	ds_read_b128 v[64:67], v240 offset:32
	ds_read_b128 v[68:71], v240 offset:9248
	ds_read_b128 v[72:75], v240 offset:18464
	ds_read_b128 v[76:79], v240 offset:27680
	v_add_u32_e32 v140, -1, v177
	v_add_u32_e32 v141, 0, v177
	v_add_u32_e32 v142, 1, v177
	v_add_u32_e32 v143, 2, v177
	v_cmp_gt_u32_e64 s[20:21], s18, v140
	v_cmp_gt_u32_e64 s[22:23], s18, v141
	v_cmp_gt_u32_e64 s[24:25], s18, v142
	v_cmp_gt_u32_e64 s[26:27], s18, v143
	v_mov_b32_e32 v136, 0
	v_mov_b32_e32 v137, 0
	v_mov_b32_e32 v138, 0
	v_mov_b32_e32 v139, 0
	v_cndmask_b32_e64 v80, -1, v80, s[20:21]
	v_cndmask_b32_e64 v81, -1, v81, s[22:23]
	v_cndmask_b32_e64 v82, -1, v82, s[24:25]
	v_cndmask_b32_e64 v83, -1, v83, s[26:27]
	v_add_u32_e32 v84, -1, v80
	v_add_u32_e32 v85, -1, v81
	v_add_u32_e32 v86, -1, v82
	v_add_u32_e32 v87, -1, v83
	s_waitcnt lgkmcnt(8)
	v_pk_add_f32 v[32:33], v[32:33], v[36:37]
	v_pk_add_f32 v[34:35], v[34:35], v[38:39]
	v_pk_add_f32 v[40:41], v[40:41], v[44:45]
	v_pk_add_f32 v[42:43], v[42:43], v[46:47]
	v_pk_add_f32 v[0:1], v[32:33], v[40:41]
	v_pk_add_f32 v[2:3], v[34:35], v[42:43]
	ds_read_b128 v[32:35], v240 offset:48
	ds_read_b128 v[36:39], v240 offset:9264
	ds_read_b128 v[40:43], v240 offset:18480
	ds_read_b128 v[44:47], v240 offset:27696
	v_cmp_le_u32_e64 s[30:31], 4, v177
	s_cmp_gt_i32 s18, 0
	s_cselect_b64 s[28:29], -1, 0
	v_cndmask_b32_e64 v1, -1, v1, s[28:29]
	s_cmp_gt_i32 s18, 1
	s_cselect_b64 s[28:29], -1, 0
	v_cndmask_b32_e64 v2, -1, v2, s[28:29]
	s_cmp_gt_i32 s18, 2
	s_cselect_b64 s[28:29], -1, 0
	v_cndmask_b32_e64 v3, -1, v3, s[28:29]
	v_cndmask_b32_e64 v92, v80, v84, s[30:31]
	v_cndmask_b32_e64 v93, v81, v85, s[30:31]
	v_cndmask_b32_e64 v94, v82, v86, s[30:31]
	v_cndmask_b32_e64 v95, v83, v87, s[30:31]
	v_cmp_gt_i32_e64 s[38:39], v1, v92
	v_cmp_gt_i32_e64 s[40:41], v1, v93
	v_cmp_gt_i32_e64 s[42:43], v1, v86
	v_cmp_gt_i32_e64 s[44:45], v1, v87
	v_addc_co_u32_e64 v136, s[36:37], 0, v136, s[38:39]
	v_addc_co_u32_e64 v137, s[36:37], 0, v137, s[40:41]
	v_addc_co_u32_e64 v138, s[36:37], 0, v138, s[42:43]
	v_addc_co_u32_e64 v139, s[36:37], 0, v139, s[44:45]
	v_cmp_gt_i32_e64 s[38:39], v2, v92
	v_cmp_gt_i32_e64 s[40:41], v2, v93
	v_cmp_gt_i32_e64 s[42:43], v2, v94
	v_cmp_gt_i32_e64 s[44:45], v2, v87
	v_addc_co_u32_e64 v136, s[36:37], 0, v136, s[38:39]
	v_addc_co_u32_e64 v137, s[36:37], 0, v137, s[40:41]
	v_addc_co_u32_e64 v138, s[36:37], 0, v138, s[42:43]
	v_addc_co_u32_e64 v139, s[36:37], 0, v139, s[44:45]
	v_cmp_gt_i32_e64 s[38:39], v3, v92
	v_cmp_gt_i32_e64 s[40:41], v3, v93
	v_cmp_gt_i32_e64 s[42:43], v3, v94
	v_cmp_gt_i32_e64 s[44:45], v3, v95
	v_addc_co_u32_e64 v136, s[36:37], 0, v136, s[38:39]
	v_addc_co_u32_e64 v137, s[36:37], 0, v137, s[40:41]
	v_addc_co_u32_e64 v138, s[36:37], 0, v138, s[42:43]
	v_addc_co_u32_e64 v139, s[36:37], 0, v139, s[44:45]
	s_waitcnt lgkmcnt(8)
	v_pk_add_f32 v[48:49], v[48:49], v[52:53]
	v_pk_add_f32 v[50:51], v[50:51], v[54:55]
	v_pk_add_f32 v[56:57], v[56:57], v[60:61]
	v_pk_add_f32 v[58:59], v[58:59], v[62:63]
	v_pk_add_f32 v[4:5], v[48:49], v[56:57]
	v_pk_add_f32 v[6:7], v[50:51], v[58:59]
	ds_read_b128 v[48:51], v240 offset:64
	ds_read_b128 v[52:55], v240 offset:9280
	ds_read_b128 v[56:59], v240 offset:18496
	ds_read_b128 v[60:63], v240 offset:27712
	v_cmp_le_u32_e64 s[30:31], 8, v177
	s_cmp_gt_i32 s18, 3
	s_cselect_b64 s[28:29], -1, 0
	v_cndmask_b32_e64 v4, -1, v4, s[28:29]
	s_cmp_gt_i32 s18, 4
	s_cselect_b64 s[28:29], -1, 0
	v_cndmask_b32_e64 v5, -1, v5, s[28:29]
	s_cmp_gt_i32 s18, 5
	s_cselect_b64 s[28:29], -1, 0
	v_cndmask_b32_e64 v6, -1, v6, s[28:29]
	s_cmp_gt_i32 s18, 6
	s_cselect_b64 s[28:29], -1, 0
	v_cndmask_b32_e64 v7, -1, v7, s[28:29]
	v_cndmask_b32_e64 v88, v80, v84, s[30:31]
	v_cndmask_b32_e64 v89, v81, v85, s[30:31]
	v_cndmask_b32_e64 v90, v82, v86, s[30:31]
	v_cndmask_b32_e64 v91, v83, v87, s[30:31]
	v_cmp_gt_i32_e64 s[38:39], v4, v88
	v_cmp_gt_i32_e64 s[40:41], v4, v93
	v_cmp_gt_i32_e64 s[42:43], v4, v94
	v_cmp_gt_i32_e64 s[44:45], v4, v95
	v_addc_co_u32_e64 v136, s[36:37], 0, v136, s[38:39]
	v_addc_co_u32_e64 v137, s[36:37], 0, v137, s[40:41]
	v_addc_co_u32_e64 v138, s[36:37], 0, v138, s[42:43]
	v_addc_co_u32_e64 v139, s[36:37], 0, v139, s[44:45]
	v_cmp_gt_i32_e64 s[38:39], v5, v88
	v_cmp_gt_i32_e64 s[40:41], v5, v89
	v_cmp_gt_i32_e64 s[42:43], v5, v94
	v_cmp_gt_i32_e64 s[44:45], v5, v95
	v_addc_co_u32_e64 v136, s[36:37], 0, v136, s[38:39]
	v_addc_co_u32_e64 v137, s[36:37], 0, v137, s[40:41]
	v_addc_co_u32_e64 v138, s[36:37], 0, v138, s[42:43]
	v_addc_co_u32_e64 v139, s[36:37], 0, v139, s[44:45]
	v_cmp_gt_i32_e64 s[38:39], v6, v88
	v_cmp_gt_i32_e64 s[40:41], v6, v89
	v_cmp_gt_i32_e64 s[42:43], v6, v90
	v_cmp_gt_i32_e64 s[44:45], v6, v95
	v_addc_co_u32_e64 v136, s[36:37], 0, v136, s[38:39]
	v_addc_co_u32_e64 v137, s[36:37], 0, v137, s[40:41]
	v_addc_co_u32_e64 v138, s[36:37], 0, v138, s[42:43]
	v_addc_co_u32_e64 v139, s[36:37], 0, v139, s[44:45]
	v_cmp_gt_i32_e64 s[38:39], v7, v88
	v_cmp_gt_i32_e64 s[40:41], v7, v89
	v_cmp_gt_i32_e64 s[42:43], v7, v90
	v_cmp_gt_i32_e64 s[44:45], v7, v91
	v_addc_co_u32_e64 v136, s[36:37], 0, v136, s[38:39]
	v_addc_co_u32_e64 v137, s[36:37], 0, v137, s[40:41]
	v_addc_co_u32_e64 v138, s[36:37], 0, v138, s[42:43]
	v_addc_co_u32_e64 v139, s[36:37], 0, v139, s[44:45]
	s_waitcnt lgkmcnt(8)
	v_pk_add_f32 v[64:65], v[64:65], v[68:69]
	v_pk_add_f32 v[66:67], v[66:67], v[70:71]
	v_pk_add_f32 v[72:73], v[72:73], v[76:77]
	v_pk_add_f32 v[74:75], v[74:75], v[78:79]
	v_pk_add_f32 v[8:9], v[64:65], v[72:73]
	v_pk_add_f32 v[10:11], v[66:67], v[74:75]
	ds_read_b128 v[64:67], v240 offset:80
	ds_read_b128 v[68:71], v240 offset:9296
	ds_read_b128 v[72:75], v240 offset:18512
	ds_read_b128 v[76:79], v240 offset:27728
	v_cmp_le_u32_e64 s[30:31], 12, v177
	s_cmp_gt_i32 s18, 7
	s_cselect_b64 s[28:29], -1, 0
	v_cndmask_b32_e64 v8, -1, v8, s[28:29]
	s_cmp_gt_i32 s18, 8
	s_cselect_b64 s[28:29], -1, 0
	v_cndmask_b32_e64 v9, -1, v9, s[28:29]
	s_cmp_gt_i32 s18, 9
	s_cselect_b64 s[28:29], -1, 0
	v_cndmask_b32_e64 v10, -1, v10, s[28:29]
	s_cmp_gt_i32 s18, 10
	s_cselect_b64 s[28:29], -1, 0
	v_cndmask_b32_e64 v11, -1, v11, s[28:29]
	v_cndmask_b32_e64 v92, v80, v84, s[30:31]
	v_cndmask_b32_e64 v93, v81, v85, s[30:31]
	v_cndmask_b32_e64 v94, v82, v86, s[30:31]
	v_cndmask_b32_e64 v95, v83, v87, s[30:31]
	v_cmp_gt_i32_e64 s[38:39], v8, v92
	v_cmp_gt_i32_e64 s[40:41], v8, v89
	v_cmp_gt_i32_e64 s[42:43], v8, v90
	v_cmp_gt_i32_e64 s[44:45], v8, v91
	v_addc_co_u32_e64 v136, s[36:37], 0, v136, s[38:39]
	v_addc_co_u32_e64 v137, s[36:37], 0, v137, s[40:41]
	v_addc_co_u32_e64 v138, s[36:37], 0, v138, s[42:43]
	v_addc_co_u32_e64 v139, s[36:37], 0, v139, s[44:45]
	v_cmp_gt_i32_e64 s[38:39], v9, v92
	v_cmp_gt_i32_e64 s[40:41], v9, v93
	v_cmp_gt_i32_e64 s[42:43], v9, v90
	v_cmp_gt_i32_e64 s[44:45], v9, v91
	v_addc_co_u32_e64 v136, s[36:37], 0, v136, s[38:39]
	v_addc_co_u32_e64 v137, s[36:37], 0, v137, s[40:41]
	v_addc_co_u32_e64 v138, s[36:37], 0, v138, s[42:43]
	v_addc_co_u32_e64 v139, s[36:37], 0, v139, s[44:45]
	v_cmp_gt_i32_e64 s[38:39], v10, v92
	v_cmp_gt_i32_e64 s[40:41], v10, v93
	v_cmp_gt_i32_e64 s[42:43], v10, v94
	v_cmp_gt_i32_e64 s[44:45], v10, v91
	v_addc_co_u32_e64 v136, s[36:37], 0, v136, s[38:39]
	v_addc_co_u32_e64 v137, s[36:37], 0, v137, s[40:41]
	v_addc_co_u32_e64 v138, s[36:37], 0, v138, s[42:43]
	v_addc_co_u32_e64 v139, s[36:37], 0, v139, s[44:45]
	v_cmp_gt_i32_e64 s[38:39], v11, v92
	v_cmp_gt_i32_e64 s[40:41], v11, v93
	v_cmp_gt_i32_e64 s[42:43], v11, v94
	v_cmp_gt_i32_e64 s[44:45], v11, v95
	v_addc_co_u32_e64 v136, s[36:37], 0, v136, s[38:39]
	v_addc_co_u32_e64 v137, s[36:37], 0, v137, s[40:41]
	v_addc_co_u32_e64 v138, s[36:37], 0, v138, s[42:43]
	v_addc_co_u32_e64 v139, s[36:37], 0, v139, s[44:45]
	s_waitcnt lgkmcnt(8)
	v_pk_add_f32 v[32:33], v[32:33], v[36:37]
	v_pk_add_f32 v[34:35], v[34:35], v[38:39]
	v_pk_add_f32 v[40:41], v[40:41], v[44:45]
	v_pk_add_f32 v[42:43], v[42:43], v[46:47]
	v_pk_add_f32 v[12:13], v[32:33], v[40:41]
	v_pk_add_f32 v[14:15], v[34:35], v[42:43]
	ds_read_b128 v[32:35], v240 offset:96
	ds_read_b128 v[36:39], v240 offset:9312
	ds_read_b128 v[40:43], v240 offset:18528
	ds_read_b128 v[44:47], v240 offset:27744
	v_cmp_le_u32_e64 s[30:31], 16, v177
	s_cmp_gt_i32 s18, 11
	s_cselect_b64 s[28:29], -1, 0
	v_cndmask_b32_e64 v12, -1, v12, s[28:29]
	s_cmp_gt_i32 s18, 12
	s_cselect_b64 s[28:29], -1, 0
	v_cndmask_b32_e64 v13, -1, v13, s[28:29]
	s_cmp_gt_i32 s18, 13
	s_cselect_b64 s[28:29], -1, 0
	v_cndmask_b32_e64 v14, -1, v14, s[28:29]
	s_cmp_gt_i32 s18, 14
	s_cselect_b64 s[28:29], -1, 0
	v_cndmask_b32_e64 v15, -1, v15, s[28:29]
	v_cndmask_b32_e64 v88, v80, v84, s[30:31]
	v_cndmask_b32_e64 v89, v81, v85, s[30:31]
	v_cndmask_b32_e64 v90, v82, v86, s[30:31]
	v_cndmask_b32_e64 v91, v83, v87, s[30:31]
	v_cmp_gt_i32_e64 s[38:39], v12, v88
	v_cmp_gt_i32_e64 s[40:41], v12, v93
	v_cmp_gt_i32_e64 s[42:43], v12, v94
	v_cmp_gt_i32_e64 s[44:45], v12, v95
	v_addc_co_u32_e64 v136, s[36:37], 0, v136, s[38:39]
	v_addc_co_u32_e64 v137, s[36:37], 0, v137, s[40:41]
	v_addc_co_u32_e64 v138, s[36:37], 0, v138, s[42:43]
	v_addc_co_u32_e64 v139, s[36:37], 0, v139, s[44:45]
	v_cmp_gt_i32_e64 s[38:39], v13, v88
	v_cmp_gt_i32_e64 s[40:41], v13, v89
	v_cmp_gt_i32_e64 s[42:43], v13, v94
	v_cmp_gt_i32_e64 s[44:45], v13, v95
	v_addc_co_u32_e64 v136, s[36:37], 0, v136, s[38:39]
	v_addc_co_u32_e64 v137, s[36:37], 0, v137, s[40:41]
	v_addc_co_u32_e64 v138, s[36:37], 0, v138, s[42:43]
	v_addc_co_u32_e64 v139, s[36:37], 0, v139, s[44:45]
	v_cmp_gt_i32_e64 s[38:39], v14, v88
	v_cmp_gt_i32_e64 s[40:41], v14, v89
	v_cmp_gt_i32_e64 s[42:43], v14, v90
	v_cmp_gt_i32_e64 s[44:45], v14, v95
	v_addc_co_u32_e64 v136, s[36:37], 0, v136, s[38:39]
	v_addc_co_u32_e64 v137, s[36:37], 0, v137, s[40:41]
	v_addc_co_u32_e64 v138, s[36:37], 0, v138, s[42:43]
	v_addc_co_u32_e64 v139, s[36:37], 0, v139, s[44:45]
	v_cmp_gt_i32_e64 s[38:39], v15, v88
	v_cmp_gt_i32_e64 s[40:41], v15, v89
	v_cmp_gt_i32_e64 s[42:43], v15, v90
	v_cmp_gt_i32_e64 s[44:45], v15, v91
	v_addc_co_u32_e64 v136, s[36:37], 0, v136, s[38:39]
	v_addc_co_u32_e64 v137, s[36:37], 0, v137, s[40:41]
	v_addc_co_u32_e64 v138, s[36:37], 0, v138, s[42:43]
	v_addc_co_u32_e64 v139, s[36:37], 0, v139, s[44:45]
	s_waitcnt lgkmcnt(8)
	v_pk_add_f32 v[48:49], v[48:49], v[52:53]
	v_pk_add_f32 v[50:51], v[50:51], v[54:55]
	v_pk_add_f32 v[56:57], v[56:57], v[60:61]
	v_pk_add_f32 v[58:59], v[58:59], v[62:63]
	v_pk_add_f32 v[16:17], v[48:49], v[56:57]
	v_pk_add_f32 v[18:19], v[50:51], v[58:59]
	ds_read_b128 v[48:51], v240 offset:112
	ds_read_b128 v[52:55], v240 offset:9328
	ds_read_b128 v[56:59], v240 offset:18544
	ds_read_b128 v[60:63], v240 offset:27760
	v_cmp_le_u32_e64 s[30:31], 20, v177
	s_cmp_gt_i32 s18, 15
	s_cselect_b64 s[28:29], -1, 0
	v_cndmask_b32_e64 v16, -1, v16, s[28:29]
	s_cmp_gt_i32 s18, 16
	s_cselect_b64 s[28:29], -1, 0
	v_cndmask_b32_e64 v17, -1, v17, s[28:29]
	s_cmp_gt_i32 s18, 17
	s_cselect_b64 s[28:29], -1, 0
	v_cndmask_b32_e64 v18, -1, v18, s[28:29]
	s_cmp_gt_i32 s18, 18
	s_cselect_b64 s[28:29], -1, 0
	v_cndmask_b32_e64 v19, -1, v19, s[28:29]
	v_cndmask_b32_e64 v92, v80, v84, s[30:31]
	v_cndmask_b32_e64 v93, v81, v85, s[30:31]
	v_cndmask_b32_e64 v94, v82, v86, s[30:31]
	v_cndmask_b32_e64 v95, v83, v87, s[30:31]
	v_cmp_gt_i32_e64 s[38:39], v16, v92
	v_cmp_gt_i32_e64 s[40:41], v16, v89
	v_cmp_gt_i32_e64 s[42:43], v16, v90
	v_cmp_gt_i32_e64 s[44:45], v16, v91
	v_addc_co_u32_e64 v136, s[36:37], 0, v136, s[38:39]
	v_addc_co_u32_e64 v137, s[36:37], 0, v137, s[40:41]
	v_addc_co_u32_e64 v138, s[36:37], 0, v138, s[42:43]
	v_addc_co_u32_e64 v139, s[36:37], 0, v139, s[44:45]
	v_cmp_gt_i32_e64 s[38:39], v17, v92
	v_cmp_gt_i32_e64 s[40:41], v17, v93
	v_cmp_gt_i32_e64 s[42:43], v17, v90
	v_cmp_gt_i32_e64 s[44:45], v17, v91
	v_addc_co_u32_e64 v136, s[36:37], 0, v136, s[38:39]
	v_addc_co_u32_e64 v137, s[36:37], 0, v137, s[40:41]
	v_addc_co_u32_e64 v138, s[36:37], 0, v138, s[42:43]
	v_addc_co_u32_e64 v139, s[36:37], 0, v139, s[44:45]
	v_cmp_gt_i32_e64 s[38:39], v18, v92
	v_cmp_gt_i32_e64 s[40:41], v18, v93
	v_cmp_gt_i32_e64 s[42:43], v18, v94
	v_cmp_gt_i32_e64 s[44:45], v18, v91
	v_addc_co_u32_e64 v136, s[36:37], 0, v136, s[38:39]
	v_addc_co_u32_e64 v137, s[36:37], 0, v137, s[40:41]
	v_addc_co_u32_e64 v138, s[36:37], 0, v138, s[42:43]
	v_addc_co_u32_e64 v139, s[36:37], 0, v139, s[44:45]
	v_cmp_gt_i32_e64 s[38:39], v19, v92
	v_cmp_gt_i32_e64 s[40:41], v19, v93
	v_cmp_gt_i32_e64 s[42:43], v19, v94
	v_cmp_gt_i32_e64 s[44:45], v19, v95
	v_addc_co_u32_e64 v136, s[36:37], 0, v136, s[38:39]
	v_addc_co_u32_e64 v137, s[36:37], 0, v137, s[40:41]
	v_addc_co_u32_e64 v138, s[36:37], 0, v138, s[42:43]
	v_addc_co_u32_e64 v139, s[36:37], 0, v139, s[44:45]
	s_waitcnt lgkmcnt(8)
	v_pk_add_f32 v[64:65], v[64:65], v[68:69]
	v_pk_add_f32 v[66:67], v[66:67], v[70:71]
	v_pk_add_f32 v[72:73], v[72:73], v[76:77]
	v_pk_add_f32 v[74:75], v[74:75], v[78:79]
	v_pk_add_f32 v[20:21], v[64:65], v[72:73]
	v_pk_add_f32 v[22:23], v[66:67], v[74:75]
	v_cmp_le_u32_e64 s[30:31], 24, v177
	s_cmp_gt_i32 s18, 19
	s_cselect_b64 s[28:29], -1, 0
	v_cndmask_b32_e64 v20, -1, v20, s[28:29]
	s_cmp_gt_i32 s18, 20
	s_cselect_b64 s[28:29], -1, 0
	v_cndmask_b32_e64 v21, -1, v21, s[28:29]
	s_cmp_gt_i32 s18, 21
	s_cselect_b64 s[28:29], -1, 0
	v_cndmask_b32_e64 v22, -1, v22, s[28:29]
	s_cmp_gt_i32 s18, 22
	s_cselect_b64 s[28:29], -1, 0
	v_cndmask_b32_e64 v23, -1, v23, s[28:29]
	v_cndmask_b32_e64 v88, v80, v84, s[30:31]
	v_cndmask_b32_e64 v89, v81, v85, s[30:31]
	v_cndmask_b32_e64 v90, v82, v86, s[30:31]
	v_cndmask_b32_e64 v91, v83, v87, s[30:31]
	v_cmp_gt_i32_e64 s[38:39], v20, v88
	v_cmp_gt_i32_e64 s[40:41], v20, v93
	v_cmp_gt_i32_e64 s[42:43], v20, v94
	v_cmp_gt_i32_e64 s[44:45], v20, v95
	v_addc_co_u32_e64 v136, s[36:37], 0, v136, s[38:39]
	v_addc_co_u32_e64 v137, s[36:37], 0, v137, s[40:41]
	v_addc_co_u32_e64 v138, s[36:37], 0, v138, s[42:43]
	v_addc_co_u32_e64 v139, s[36:37], 0, v139, s[44:45]
	v_cmp_gt_i32_e64 s[38:39], v21, v88
	v_cmp_gt_i32_e64 s[40:41], v21, v89
	v_cmp_gt_i32_e64 s[42:43], v21, v94
	v_cmp_gt_i32_e64 s[44:45], v21, v95
	v_addc_co_u32_e64 v136, s[36:37], 0, v136, s[38:39]
	v_addc_co_u32_e64 v137, s[36:37], 0, v137, s[40:41]
	v_addc_co_u32_e64 v138, s[36:37], 0, v138, s[42:43]
	v_addc_co_u32_e64 v139, s[36:37], 0, v139, s[44:45]
	v_cmp_gt_i32_e64 s[38:39], v22, v88
	v_cmp_gt_i32_e64 s[40:41], v22, v89
	v_cmp_gt_i32_e64 s[42:43], v22, v90
	v_cmp_gt_i32_e64 s[44:45], v22, v95
	v_addc_co_u32_e64 v136, s[36:37], 0, v136, s[38:39]
	v_addc_co_u32_e64 v137, s[36:37], 0, v137, s[40:41]
	v_addc_co_u32_e64 v138, s[36:37], 0, v138, s[42:43]
	v_addc_co_u32_e64 v139, s[36:37], 0, v139, s[44:45]
	v_cmp_gt_i32_e64 s[38:39], v23, v88
	v_cmp_gt_i32_e64 s[40:41], v23, v89
	v_cmp_gt_i32_e64 s[42:43], v23, v90
	v_cmp_gt_i32_e64 s[44:45], v23, v91
	v_addc_co_u32_e64 v136, s[36:37], 0, v136, s[38:39]
	v_addc_co_u32_e64 v137, s[36:37], 0, v137, s[40:41]
	v_addc_co_u32_e64 v138, s[36:37], 0, v138, s[42:43]
	v_addc_co_u32_e64 v139, s[36:37], 0, v139, s[44:45]
	s_waitcnt lgkmcnt(4)
	v_pk_add_f32 v[32:33], v[32:33], v[36:37]
	v_pk_add_f32 v[34:35], v[34:35], v[38:39]
	v_pk_add_f32 v[40:41], v[40:41], v[44:45]
	v_pk_add_f32 v[42:43], v[42:43], v[46:47]
	v_pk_add_f32 v[24:25], v[32:33], v[40:41]
	v_pk_add_f32 v[26:27], v[34:35], v[42:43]
	v_cmp_le_u32_e64 s[30:31], 28, v177
	s_cmp_gt_i32 s18, 23
	s_cselect_b64 s[28:29], -1, 0
	v_cndmask_b32_e64 v24, -1, v24, s[28:29]
	s_cmp_gt_i32 s18, 24
	s_cselect_b64 s[28:29], -1, 0
	v_cndmask_b32_e64 v25, -1, v25, s[28:29]
	s_cmp_gt_i32 s18, 25
	s_cselect_b64 s[28:29], -1, 0
	v_cndmask_b32_e64 v26, -1, v26, s[28:29]
	s_cmp_gt_i32 s18, 26
	s_cselect_b64 s[28:29], -1, 0
	v_cndmask_b32_e64 v27, -1, v27, s[28:29]
	v_cndmask_b32_e64 v92, v80, v84, s[30:31]
	v_cndmask_b32_e64 v93, v81, v85, s[30:31]
	v_cndmask_b32_e64 v94, v82, v86, s[30:31]
	v_cndmask_b32_e64 v95, v83, v87, s[30:31]
	v_cmp_gt_i32_e64 s[38:39], v24, v92
	v_cmp_gt_i32_e64 s[40:41], v24, v89
	v_cmp_gt_i32_e64 s[42:43], v24, v90
	v_cmp_gt_i32_e64 s[44:45], v24, v91
	v_addc_co_u32_e64 v136, s[36:37], 0, v136, s[38:39]
	v_addc_co_u32_e64 v137, s[36:37], 0, v137, s[40:41]
	v_addc_co_u32_e64 v138, s[36:37], 0, v138, s[42:43]
	v_addc_co_u32_e64 v139, s[36:37], 0, v139, s[44:45]
	v_cmp_gt_i32_e64 s[38:39], v25, v92
	v_cmp_gt_i32_e64 s[40:41], v25, v93
	v_cmp_gt_i32_e64 s[42:43], v25, v90
	v_cmp_gt_i32_e64 s[44:45], v25, v91
	v_addc_co_u32_e64 v136, s[36:37], 0, v136, s[38:39]
	v_addc_co_u32_e64 v137, s[36:37], 0, v137, s[40:41]
	v_addc_co_u32_e64 v138, s[36:37], 0, v138, s[42:43]
	v_addc_co_u32_e64 v139, s[36:37], 0, v139, s[44:45]
	v_cmp_gt_i32_e64 s[38:39], v26, v92
	v_cmp_gt_i32_e64 s[40:41], v26, v93
	v_cmp_gt_i32_e64 s[42:43], v26, v94
	v_cmp_gt_i32_e64 s[44:45], v26, v91
	v_addc_co_u32_e64 v136, s[36:37], 0, v136, s[38:39]
	v_addc_co_u32_e64 v137, s[36:37], 0, v137, s[40:41]
	v_addc_co_u32_e64 v138, s[36:37], 0, v138, s[42:43]
	v_addc_co_u32_e64 v139, s[36:37], 0, v139, s[44:45]
	v_cmp_gt_i32_e64 s[38:39], v27, v92
	v_cmp_gt_i32_e64 s[40:41], v27, v93
	v_cmp_gt_i32_e64 s[42:43], v27, v94
	v_cmp_gt_i32_e64 s[44:45], v27, v95
	v_addc_co_u32_e64 v136, s[36:37], 0, v136, s[38:39]
	v_addc_co_u32_e64 v137, s[36:37], 0, v137, s[40:41]
	v_addc_co_u32_e64 v138, s[36:37], 0, v138, s[42:43]
	v_addc_co_u32_e64 v139, s[36:37], 0, v139, s[44:45]
	s_waitcnt lgkmcnt(0)
	v_pk_add_f32 v[48:49], v[48:49], v[52:53]
	v_pk_add_f32 v[50:51], v[50:51], v[54:55]
	v_pk_add_f32 v[56:57], v[56:57], v[60:61]
	v_pk_add_f32 v[58:59], v[58:59], v[62:63]
	v_pk_add_f32 v[28:29], v[48:49], v[56:57]
	v_pk_add_f32 v[30:31], v[50:51], v[58:59]
	s_cmp_gt_i32 s18, 27
	s_cselect_b64 s[28:29], -1, 0
	v_cndmask_b32_e64 v28, -1, v28, s[28:29]
	s_cmp_gt_i32 s18, 28
	s_cselect_b64 s[28:29], -1, 0
	v_cndmask_b32_e64 v29, -1, v29, s[28:29]
	v_cmp_gt_i32_e64 s[38:39], v28, v80
	v_cmp_gt_i32_e64 s[40:41], v28, v93
	v_cmp_gt_i32_e64 s[42:43], v28, v94
	v_cmp_gt_i32_e64 s[44:45], v28, v95
	v_addc_co_u32_e64 v136, s[36:37], 0, v136, s[38:39]
	v_addc_co_u32_e64 v137, s[36:37], 0, v137, s[40:41]
	v_addc_co_u32_e64 v138, s[36:37], 0, v138, s[42:43]
	v_addc_co_u32_e64 v139, s[36:37], 0, v139, s[44:45]
	v_cmp_gt_i32_e64 s[38:39], v29, v80
	v_cmp_gt_i32_e64 s[40:41], v29, v81
	v_cmp_gt_i32_e64 s[42:43], v29, v94
	v_cmp_gt_i32_e64 s[44:45], v29, v95
	v_addc_co_u32_e64 v136, s[36:37], 0, v136, s[38:39]
	v_addc_co_u32_e64 v137, s[36:37], 0, v137, s[40:41]
	v_addc_co_u32_e64 v138, s[36:37], 0, v138, s[42:43]
	v_addc_co_u32_e64 v139, s[36:37], 0, v139, s[44:45]
	v_cmp_gt_i32_e64 s[38:39], s17, v136
	v_cmp_gt_i32_e64 s[40:41], s17, v137
	v_cmp_gt_i32_e64 s[42:43], s17, v138
	v_cmp_gt_i32_e64 s[44:45], s17, v139
	s_and_b64 s[38:39], s[38:39], s[20:21]
	s_and_b64 s[40:41], s[40:41], s[22:23]
	s_and_b64 s[42:43], s[42:43], s[24:25]
	s_and_b64 s[44:45], s[44:45], s[26:27]
	v_cndmask_b32_e64 v140, 0, v231, s[38:39]
	v_cndmask_b32_e64 v141, 0, v232, s[40:41]
	v_cndmask_b32_e64 v142, 0, v234, s[42:43]
	v_cndmask_b32_e64 v143, 0, v236, s[44:45]
	v_or3_b32 v140, v140, v141, v142
	v_or_b32_e32 v140, v140, v143
	s_nop 1
	v_or_b32_dpp v141, v140, v140 quad_perm:[1,0,3,2] row_mask:0xf bank_mask:0xf
	s_nop 1
	v_or_b32_dpp v140, v141, v141 quad_perm:[2,3,0,1] row_mask:0xf bank_mask:0xf
	s_nop 1
	v_or_b32_dpp v141, v140, v140 row_half_mirror row_mask:0xf bank_mask:0xf
	v_cmp_eq_u32_e32 vcc, 0, v177
	v_or_b32_e32 v141, s16, v141
	s_and_saveexec_b64 s[0:1], vcc
	s_cbranch_execz .LBB0_398
	ds_write_b32 v179, v141
